# baseline (speedup 1.0000x reference)
; #define PG8_STAGE(bufoff, gbase, voff) do { _Pragma("unroll") for (int _i = 0; _i < 2; ++_i) \
;         __builtin_amdgcn_global_load_lds((const unsigned*)((const char*)(gbase) + (voff)[_i]), (PG8_LAS unsigned*)(lds + (bufoff) + ldsw + _i * 8192), 16, 0, 0); } while (0)
; #define PG8_LDA(dst, b, h) do { _Pragma("unroll") for (int m = 0; m < 4; ++m) _Pragma("unroll") for (int k = 0; k < 2; ++k) dst[m][k] = *(const PG8_LAS bf16x8*)(lds + PG8_SA(b, h) + aoff + m * 2048 + k * 1024); } while (0)
; #define PG8_LDB(dst, b, h) do { _Pragma("unroll") for (int n = 0; n < 2; ++n) _Pragma("unroll") for (int k = 0; k < 2; ++k) dst[n][k] = *(const PG8_LAS bf16x8*)(lds + PG8_SB(b, h) + boff + n * 2048 + k * 1024); } while (0)
; #define PG8_BAR __builtin_amdgcn_s_barrier()
;     __host__ __device__ bool next(int i, Unit& u) const {
;         const long L = (long)i * G + c; if (L >= nwg) return false;
;         int wgid = (int)L; { const int q = nwg / NXCD, r = nwg % NXCD, xcd = wgid % NXCD, off = wgid / NXCD; wgid = (xcd < r ? xcd * (q + 1) : r * (q + 1) + (xcd - r) * q) + off; }
;         const int nig = WGM * nN, gid = wgid / nig, fm = gid * WGM, gsz = (nM - fm) < WGM ? (nM - fm) : WGM;
;         u.pm = fm + ((wgid % nig) % gsz); u.pn = (wgid % nig) / gsz; return true;
; template <class Epi, class Sched, bool ALIGN_EPI = false, bool SP2 = false>
; __device__ __forceinline__ void gemm_phase(PG8_LAS unsigned char* lds, const Gemm g, const Sched& S, const Epi& E) {
;     ...
;         const bool has_next = S.next(ui + 1, nxt);
;         const char* nA = has_next ? (const char*)g.A + (size_t)nxt.pm * tstep : cA; const char* nB = has_next ? (const char*)g.Bt + (size_t)nxt.pn * tstep : cB;
;         for (int t = 0; t < nt; t += 2) {
;             const bool last = (t == nt - 2);
;             const char* a1 = cA + (size_t)(t + 1) * kstep;
;             const char* a2 = last ? nA : cA + (size_t)(t + 2) * kstep; const char* b2 = last ? nB : cB + (size_t)(t + 2) * kstep;
;             const char* a3 = a2 + kstep; const char* b3 = b2 + kstep;
;             if (last && has_next) S.a_ready(nxt);
;             if constexpr (SP2) {
;             PG8_LDB(B0, 0, 0); PG8_LDB(B1, 0, 1); PG8_SCHED; PG8_LDA(At, 0, 0); PG8_STAGE(PG8_SA(1, 1), a1 + hstep, voffA);
;             PG8_WAIT_V(8); PG8_WAIT_L(0); PG8_BAR; PG8_MMA(0, 0, At, B0); PG8_MMA(0, 1, At, B1); PG8_BAR; PG8_SCHED;
.LBB0_202:
	s_waitcnt lgkmcnt(0)
	v_add_u32_e32 v204, 0x10000, v238
	ds_read_b128 v[80:83], v204
	ds_read_b128 v[88:91], v204 offset:1024
	ds_read_b128 v[104:107], v204 offset:2048
	ds_read_b128 v[108:111], v204 offset:3072
	ds_read_b128 v[128:131], v204 offset:16384
	ds_read_b128 v[132:135], v204 offset:17408
	ds_read_b128 v[152:155], v204 offset:18432
	ds_read_b128 v[156:159], v204 offset:19456
	ds_read_b128 v[160:163], v240
	ds_read_b128 v[164:167], v240 offset:1024
	ds_read_b128 v[168:171], v240 offset:2048
	ds_read_b128 v[172:175], v240 offset:3072
	ds_read_b128 v[176:179], v240 offset:4096
	ds_read_b128 v[180:183], v240 offset:5120
	ds_read_b128 v[184:187], v240 offset:6144
	ds_read_b128 v[200:203], v240 offset:7168
	s_add_i32 s81, s81, 1
	s_mul_i32 s3, s81, s86
	s_mul_hi_u32 s6, s81, s14
	s_add_i32 s6, s6, s3
	s_mul_i32 s3, s81, s14
	s_add_u32 s62, s3, s2
	s_addc_u32 s63, s6, s33
	v_mov_b64_e32 v[0:1], s[98:99]
	v_cmp_ge_i64_e32 vcc, s[62:63], v[0:1]
	v_cmp_lt_i64_e64 s[6:7], s[62:63], v[0:1]
	s_cbranch_vccnz .LBB0_204
	s_ashr_i32 s3, s62, 31
	s_lshr_b32 s3, s3, 29
	s_add_i32 s3, s62, s3
	s_ashr_i32 s9, s3, 3
	s_and_b32 s3, s3, -8
	s_sub_i32 s3, s62, s3
	s_lshr_b32 s36, s3, 31
	s_add_i32 s36, s15, s36
	s_mul_i32 s3, s36, s3
	s_add_i32 s3, s3, s9
	s_ashr_i32 s9, s3, 31
	s_lshr_b32 s9, s9, 26
	s_add_i32 s9, s3, s9
	s_ashr_i32 s36, s9, 6
	s_lshl_b32 s36, s36, 3
	s_sub_i32 s37, s15, s36
	s_min_i32 s37, s37, 8
	s_abs_i32 s38, s37
	v_cvt_f32_u32_e32 v0, s38
	s_sub_i32 s40, 0, s38
	s_andn2_b32 s9, s9, 63
	s_sub_i32 s3, s3, s9
	v_rcp_iflag_f32_e32 v0, v0
	s_abs_i32 s9, s3
	s_xor_b32 s39, s3, s37
	s_ashr_i32 s39, s39, 31
	v_mul_f32_e32 v0, 0x4f7ffffe, v0
	v_cvt_u32_f32_e32 v0, v0
	s_nop 0
	v_readfirstlane_b32 s41, v0
	s_mul_i32 s40, s40, s41
	s_mul_hi_u32 s40, s41, s40
	s_add_i32 s41, s41, s40
	s_mul_hi_u32 s40, s9, s41
	s_mul_i32 s41, s40, s38
	s_sub_i32 s9, s9, s41
	s_add_i32 s42, s40, 1
	s_sub_i32 s41, s9, s38
	s_cmp_ge_u32 s9, s38
	s_cselect_b32 s40, s42, s40
	s_cselect_b32 s9, s41, s9
	s_add_i32 s41, s40, 1
	s_cmp_ge_u32 s9, s38
	s_cselect_b32 s9, s41, s40
	s_xor_b32 s9, s9, s39
	s_sub_i32 s58, s9, s39
	s_mul_i32 s9, s58, s37
	s_sub_i32 s3, s3, s9
	s_add_i32 s60, s3, s36
.LBB0_204:
	s_ashr_i32 s61, s60, 31
	s_lshl_b64 s[36:37], s[60:61], 20
	s_add_u32 s62, s45, s36
	s_addc_u32 s63, s44, s37
	s_and_b64 s[36:37], s[6:7], exec
	s_cselect_b32 s9, s63, s69
	s_cselect_b32 s61, s62, s68
	s_ashr_i32 s59, s58, 31
	s_lshl_b64 s[36:37], s[58:59], 20
	s_add_u32 s64, s54, s36
	s_addc_u32 s65, s55, s37
	s_and_b64 s[36:37], s[6:7], exec
	s_cselect_b32 s59, s65, s71
	s_cselect_b32 s87, s64, s70
	s_add_u32 s68, s68, 0x80080
	s_addc_u32 s69, s69, 0
	s_add_u32 s3, s70, 0x100
	s_addc_u32 s88, s71, 0
	s_mov_b32 s89, -2
	s_nop 0
	s_add_u32 s36, s68, 0xfff80080
	s_addc_u32 s37, s69, -1
	s_add_i32 s38, 0, 0x10000
	s_cmp_eq_u32 s89, 28
	s_cselect_b32 s73, s9, s37
	s_cselect_b32 s72, s61, s36
	s_cselect_b32 s71, s59, s88
	s_cselect_b32 s70, s87, s3
	s_add_i32 s39, 0, 0x14000
	s_add_i32 m0, s67, 0xc000
	global_load_lds_dwordx4 v196, s[68:69]
	s_add_i32 m0, s67, 0xe000
	s_nop 0
	global_load_lds_dwordx4 v198, s[68:69]
	s_waitcnt lgkmcnt(0)
	s_barrier
	s_setprio 1
	s_waitcnt lgkmcnt(0)
	v_mfma_f32_16x16x32_bf16 v[148:151], v[80:83], v[160:163], 0
	v_mfma_f32_16x16x32_bf16 v[148:151], v[88:91], v[164:167], v[148:151]
	v_mfma_f32_16x16x32_bf16 v[144:147], v[104:107], v[160:163], 0
	v_mfma_f32_16x16x32_bf16 v[144:147], v[108:111], v[164:167], v[144:147]
	v_mfma_f32_16x16x32_bf16 v[124:127], v[80:83], v[168:171], 0
	v_mfma_f32_16x16x32_bf16 v[124:127], v[88:91], v[172:175], v[124:127]
	v_mfma_f32_16x16x32_bf16 v[120:123], v[104:107], v[168:171], 0
	v_mfma_f32_16x16x32_bf16 v[120:123], v[108:111], v[172:175], v[120:123]
	v_mfma_f32_16x16x32_bf16 v[100:103], v[80:83], v[176:179], 0
	v_mfma_f32_16x16x32_bf16 v[100:103], v[88:91], v[180:183], v[100:103]
	v_mfma_f32_16x16x32_bf16 v[96:99], v[104:107], v[176:179], 0
	v_mfma_f32_16x16x32_bf16 v[96:99], v[108:111], v[180:183], v[96:99]
	v_mfma_f32_16x16x32_bf16 v[76:79], v[80:83], v[184:187], 0
	v_mfma_f32_16x16x32_bf16 v[76:79], v[88:91], v[200:203], v[76:79]
	v_mfma_f32_16x16x32_bf16 v[72:75], v[104:107], v[184:187], 0
	v_mfma_f32_16x16x32_bf16 v[72:75], v[108:111], v[200:203], v[72:75]
	s_setprio 0
	s_setprio 1
	v_mfma_f32_16x16x32_bf16 v[140:143], v[128:131], v[160:163], 0
	v_mfma_f32_16x16x32_bf16 v[140:143], v[132:135], v[164:167], v[140:143]
	v_mfma_f32_16x16x32_bf16 v[136:139], v[152:155], v[160:163], 0
	v_mfma_f32_16x16x32_bf16 v[136:139], v[156:159], v[164:167], v[136:139]
	v_mfma_f32_16x16x32_bf16 v[116:119], v[128:131], v[168:171], 0
	v_mfma_f32_16x16x32_bf16 v[116:119], v[132:135], v[172:175], v[116:119]
	v_mfma_f32_16x16x32_bf16 v[112:115], v[152:155], v[168:171], 0
	v_mfma_f32_16x16x32_bf16 v[112:115], v[156:159], v[172:175], v[112:115]
	v_mfma_f32_16x16x32_bf16 v[92:95], v[128:131], v[176:179], 0
	v_mfma_f32_16x16x32_bf16 v[92:95], v[132:135], v[180:183], v[92:95]
	v_mfma_f32_16x16x32_bf16 v[84:87], v[152:155], v[176:179], 0
	v_mfma_f32_16x16x32_bf16 v[84:87], v[156:159], v[180:183], v[84:87]
	v_mfma_f32_16x16x32_bf16 v[68:71], v[128:131], v[184:187], 0
	v_mfma_f32_16x16x32_bf16 v[68:71], v[132:135], v[200:203], v[68:71]
	v_mfma_f32_16x16x32_bf16 v[64:67], v[152:155], v[184:187], 0
	v_mfma_f32_16x16x32_bf16 v[64:67], v[156:159], v[200:203], v[64:67]
	s_setprio 0
	s_barrier
; #define PG8_STAGE(bufoff, gbase, voff) do { _Pragma("unroll") for (int _i = 0; _i < 2; ++_i) \
;         __builtin_amdgcn_global_load_lds((const unsigned*)((const char*)(gbase) + (voff)[_i]), (PG8_LAS unsigned*)(lds + (bufoff) + ldsw + _i * 8192), 16, 0, 0); } while (0)
; #define PG8_LDA(dst, b, h) do { _Pragma("unroll") for (int m = 0; m < 4; ++m) _Pragma("unroll") for (int k = 0; k < 2; ++k) dst[m][k] = *(const PG8_LAS bf16x8*)(lds + PG8_SA(b, h) + aoff + m * 2048 + k * 1024); } while (0)
; #define PG8_LDB(dst, b, h) do { _Pragma("unroll") for (int n = 0; n < 2; ++n) _Pragma("unroll") for (int k = 0; k < 2; ++k) dst[n][k] = *(const PG8_LAS bf16x8*)(lds + PG8_SB(b, h) + boff + n * 2048 + k * 1024); } while (0)
; #define PG8_MMA(ai, bj, At, Bt) do { __builtin_amdgcn_s_setprio(1); _Pragma("unroll") for (int m = 0; m < 4; ++m) _Pragma("unroll") for (int n = 0; n < 2; ++n) _Pragma("unroll") for (int k = 0; k < 2; ++k) \
;         acc[ai][bj][m][n] = __builtin_amdgcn_mfma_f32_16x16x32_bf16(Bt[n][k], At[m][k], acc[ai][bj][m][n], 0, 0, 0); __builtin_amdgcn_s_setprio(0); } while (0)
; #define PG8_WAIT_V(n) asm volatile("s_waitcnt vmcnt(" #n ")" ::: "memory")
; #define PG8_WAIT_L(n) asm volatile("s_waitcnt lgkmcnt(" #n ")" ::: "memory")
; #define PG8_BAR __builtin_amdgcn_s_barrier()
; #define PG8_SCHED __builtin_amdgcn_sched_barrier(0)
; template <class Epi, class Sched, bool ALIGN_EPI = false, bool SP2 = false>
; __device__ __forceinline__ void gemm_phase(PG8_LAS unsigned char* lds, const Gemm g, const Sched& S, const Epi& E) {
;     ...
;             PG8_LDA(At, 0, 1); PG8_STAGE(PG8_SB(0, 0), b2, voffB); PG8_STAGE(PG8_SB(0, 1), b2 + hstep, voffB); PG8_STAGE(PG8_SA(0, 0), a2, voffA);
;             PG8_WAIT_V(8); PG8_WAIT_L(0); PG8_BAR; PG8_MMA(1, 0, At, B0); PG8_MMA(1, 1, At, B1); PG8_BAR; PG8_SCHED;
;             PG8_LDB(B0, 1, 0); PG8_LDB(B1, 1, 1); PG8_SCHED; PG8_LDA(At, 1, 0); PG8_STAGE(PG8_SA(0, 1), a2 + hstep, voffA);
;             PG8_WAIT_V(8); PG8_WAIT_L(0); PG8_BAR; PG8_MMA(0, 0, At, B0); PG8_MMA(0, 1, At, B1); PG8_BAR; PG8_SCHED;
	s_add_i32 s36, s38, s75
	s_mov_b32 m0, s36
	ds_read_b128 v[160:163], v240 offset:16384
	ds_read_b128 v[164:167], v240 offset:17408
	ds_read_b128 v[168:171], v240 offset:18432
	ds_read_b128 v[172:175], v240 offset:19456
	ds_read_b128 v[176:179], v240 offset:20480
	ds_read_b128 v[180:183], v240 offset:21504
	ds_read_b128 v[184:187], v240 offset:22528
	ds_read_b128 v[200:203], v240 offset:23552
	global_load_lds_dwordx4 v188, s[70:71]
	s_add_i32 m0, s36, 0x2000
	s_add_u32 s36, s70, 0x80000
	s_addc_u32 s37, s71, 0
	s_add_i32 s38, s39, s75
	global_load_lds_dwordx4 v194, s[70:71]
	s_mov_b32 m0, s38
	s_nop 0
	global_load_lds_dwordx4 v188, s[36:37]
	s_add_i32 m0, s38, 0x2000
	s_nop 0
	global_load_lds_dwordx4 v194, s[36:37]
	s_mov_b32 m0, s67
	s_nop 0
	global_load_lds_dwordx4 v188, s[72:73]
	s_mov_b32 m0, s76
	s_nop 0
	global_load_lds_dwordx4 v194, s[72:73]
	s_waitcnt lgkmcnt(0)
	s_barrier
	s_setprio 1
	s_waitcnt lgkmcnt(0)
	v_mfma_f32_16x16x32_bf16 v[60:63], v[80:83], v[160:163], 0
	v_mfma_f32_16x16x32_bf16 v[60:63], v[88:91], v[164:167], v[60:63]
	v_mfma_f32_16x16x32_bf16 v[56:59], v[104:107], v[160:163], 0
	v_mfma_f32_16x16x32_bf16 v[56:59], v[108:111], v[164:167], v[56:59]
	v_mfma_f32_16x16x32_bf16 v[44:47], v[80:83], v[168:171], 0
	v_mfma_f32_16x16x32_bf16 v[44:47], v[88:91], v[172:175], v[44:47]
	v_mfma_f32_16x16x32_bf16 v[40:43], v[104:107], v[168:171], 0
	v_mfma_f32_16x16x32_bf16 v[40:43], v[108:111], v[172:175], v[40:43]
	v_mfma_f32_16x16x32_bf16 v[28:31], v[80:83], v[176:179], 0
	v_mfma_f32_16x16x32_bf16 v[28:31], v[88:91], v[180:183], v[28:31]
	v_mfma_f32_16x16x32_bf16 v[24:27], v[104:107], v[176:179], 0
	v_mfma_f32_16x16x32_bf16 v[24:27], v[108:111], v[180:183], v[24:27]
	v_mfma_f32_16x16x32_bf16 v[12:15], v[80:83], v[184:187], 0
	v_mfma_f32_16x16x32_bf16 v[12:15], v[88:91], v[200:203], v[12:15]
	v_mfma_f32_16x16x32_bf16 v[8:11], v[104:107], v[184:187], 0
	v_mfma_f32_16x16x32_bf16 v[8:11], v[108:111], v[200:203], v[8:11]
	s_setprio 0
	s_setprio 1
	v_mfma_f32_16x16x32_bf16 v[52:55], v[128:131], v[160:163], 0
	v_mfma_f32_16x16x32_bf16 v[52:55], v[132:135], v[164:167], v[52:55]
	v_mfma_f32_16x16x32_bf16 v[48:51], v[152:155], v[160:163], 0
	v_mfma_f32_16x16x32_bf16 v[48:51], v[156:159], v[164:167], v[48:51]
	v_mfma_f32_16x16x32_bf16 v[36:39], v[128:131], v[168:171], 0
	v_mfma_f32_16x16x32_bf16 v[36:39], v[132:135], v[172:175], v[36:39]
	v_mfma_f32_16x16x32_bf16 v[32:35], v[152:155], v[168:171], 0
	v_mfma_f32_16x16x32_bf16 v[32:35], v[156:159], v[172:175], v[32:35]
	v_mfma_f32_16x16x32_bf16 v[20:23], v[128:131], v[176:179], 0
	v_mfma_f32_16x16x32_bf16 v[20:23], v[132:135], v[180:183], v[20:23]
	v_mfma_f32_16x16x32_bf16 v[16:19], v[152:155], v[176:179], 0
	v_mfma_f32_16x16x32_bf16 v[16:19], v[156:159], v[180:183], v[16:19]
	v_mfma_f32_16x16x32_bf16 v[4:7], v[128:131], v[184:187], 0
	v_mfma_f32_16x16x32_bf16 v[4:7], v[132:135], v[200:203], v[4:7]
	v_mfma_f32_16x16x32_bf16 v[0:3], v[152:155], v[184:187], 0
	v_mfma_f32_16x16x32_bf16 v[0:3], v[156:159], v[200:203], v[0:3]
	s_setprio 0
	s_barrier
	s_add_i32 s38, 0, 0x18000
	s_add_i32 s39, 0, 0x1c000
	ds_read_b128 v[80:83], v204 offset:32768
	ds_read_b128 v[88:91], v204 offset:33792
	ds_read_b128 v[104:107], v204 offset:34816
	ds_read_b128 v[108:111], v204 offset:35840
	ds_read_b128 v[128:131], v204 offset:49152
	ds_read_b128 v[132:135], v204 offset:50176
	ds_read_b128 v[152:155], v204 offset:51200
	ds_read_b128 v[156:159], v204 offset:52224
	s_add_u32 s36, s72, 0x80000
	s_addc_u32 s37, s73, 0
	s_mov_b32 m0, s77
	ds_read_b128 v[160:163], v240 offset:32768
	ds_read_b128 v[164:167], v240 offset:33792
	ds_read_b128 v[168:171], v240 offset:34816
	ds_read_b128 v[172:175], v240 offset:35840
	ds_read_b128 v[176:179], v240 offset:36864
	ds_read_b128 v[180:183], v240 offset:37888
	ds_read_b128 v[184:187], v240 offset:38912
	ds_read_b128 v[200:203], v240 offset:39936
	global_load_lds_dwordx4 v188, s[36:37]
	s_mov_b32 m0, s78
	s_nop 0
	global_load_lds_dwordx4 v194, s[36:37]
	s_waitcnt vmcnt(8)
	s_waitcnt lgkmcnt(0)
	s_barrier
; #define PG8_STAGE(bufoff, gbase, voff) do { _Pragma("unroll") for (int _i = 0; _i < 2; ++_i) \
;         __builtin_amdgcn_global_load_lds((const unsigned*)((const char*)(gbase) + (voff)[_i]), (PG8_LAS unsigned*)(lds + (bufoff) + ldsw + _i * 8192), 16, 0, 0); } while (0)
; #define PG8_LDA(dst, b, h) do { _Pragma("unroll") for (int m = 0; m < 4; ++m) _Pragma("unroll") for (int k = 0; k < 2; ++k) dst[m][k] = *(const PG8_LAS bf16x8*)(lds + PG8_SA(b, h) + aoff + m * 2048 + k * 1024); } while (0)
; #define PG8_MMA(ai, bj, At, Bt) do { __builtin_amdgcn_s_setprio(1); _Pragma("unroll") for (int m = 0; m < 4; ++m) _Pragma("unroll") for (int n = 0; n < 2; ++n) _Pragma("unroll") for (int k = 0; k < 2; ++k) \
;         acc[ai][bj][m][n] = __builtin_amdgcn_mfma_f32_16x16x32_bf16(Bt[n][k], At[m][k], acc[ai][bj][m][n], 0, 0, 0); __builtin_amdgcn_s_setprio(0); } while (0)
; #define PG8_WAIT_V(n) asm volatile("s_waitcnt vmcnt(" #n ")" ::: "memory")
; #define PG8_WAIT_L(n) asm volatile("s_waitcnt lgkmcnt(" #n ")" ::: "memory")
; #define PG8_BAR __builtin_amdgcn_s_barrier()
; #define PG8_SCHED __builtin_amdgcn_sched_barrier(0)
; template <class Epi, class Sched, bool ALIGN_EPI = false, bool SP2 = false>
; __device__ __forceinline__ void gemm_phase(PG8_LAS unsigned char* lds, const Gemm g, const Sched& S, const Epi& E) {
;     ...
;             PG8_WAIT_V(8); PG8_WAIT_L(0); PG8_BAR; PG8_MMA(0, 0, At, B0); PG8_MMA(0, 1, At, B1); PG8_BAR; PG8_SCHED;
;             PG8_LDA(At, 1, 1); PG8_STAGE(PG8_SB(1, 0), b3, voffB); PG8_STAGE(PG8_SB(1, 1), b3 + hstep, voffB); PG8_STAGE(PG8_SA(1, 0), a3, voffA);
;             PG8_WAIT_V(8); PG8_WAIT_L(0); PG8_BAR; PG8_MMA(1, 0, At, B0); PG8_MMA(1, 1, At, B1); PG8_BAR; PG8_SCHED;
	s_setprio 1
	s_waitcnt lgkmcnt(0)
	v_mfma_f32_16x16x32_bf16 v[148:151], v[80:83], v[160:163], v[148:151]
	v_mfma_f32_16x16x32_bf16 v[148:151], v[88:91], v[164:167], v[148:151]
	v_mfma_f32_16x16x32_bf16 v[144:147], v[104:107], v[160:163], v[144:147]
	v_mfma_f32_16x16x32_bf16 v[144:147], v[108:111], v[164:167], v[144:147]
	v_mfma_f32_16x16x32_bf16 v[124:127], v[80:83], v[168:171], v[124:127]
	v_mfma_f32_16x16x32_bf16 v[124:127], v[88:91], v[172:175], v[124:127]
	v_mfma_f32_16x16x32_bf16 v[120:123], v[104:107], v[168:171], v[120:123]
	v_mfma_f32_16x16x32_bf16 v[120:123], v[108:111], v[172:175], v[120:123]
	v_mfma_f32_16x16x32_bf16 v[100:103], v[80:83], v[176:179], v[100:103]
	v_mfma_f32_16x16x32_bf16 v[100:103], v[88:91], v[180:183], v[100:103]
	v_mfma_f32_16x16x32_bf16 v[96:99], v[104:107], v[176:179], v[96:99]
	v_mfma_f32_16x16x32_bf16 v[96:99], v[108:111], v[180:183], v[96:99]
	v_mfma_f32_16x16x32_bf16 v[76:79], v[80:83], v[184:187], v[76:79]
	v_mfma_f32_16x16x32_bf16 v[76:79], v[88:91], v[200:203], v[76:79]
	v_mfma_f32_16x16x32_bf16 v[72:75], v[104:107], v[184:187], v[72:75]
	v_mfma_f32_16x16x32_bf16 v[72:75], v[108:111], v[200:203], v[72:75]
	s_setprio 0
	s_setprio 1
	v_mfma_f32_16x16x32_bf16 v[140:143], v[128:131], v[160:163], v[140:143]
	v_mfma_f32_16x16x32_bf16 v[140:143], v[132:135], v[164:167], v[140:143]
	v_mfma_f32_16x16x32_bf16 v[136:139], v[152:155], v[160:163], v[136:139]
	v_mfma_f32_16x16x32_bf16 v[136:139], v[156:159], v[164:167], v[136:139]
	v_mfma_f32_16x16x32_bf16 v[116:119], v[128:131], v[168:171], v[116:119]
	v_mfma_f32_16x16x32_bf16 v[116:119], v[132:135], v[172:175], v[116:119]
	v_mfma_f32_16x16x32_bf16 v[112:115], v[152:155], v[168:171], v[112:115]
	v_mfma_f32_16x16x32_bf16 v[112:115], v[156:159], v[172:175], v[112:115]
	v_mfma_f32_16x16x32_bf16 v[92:95], v[128:131], v[176:179], v[92:95]
	v_mfma_f32_16x16x32_bf16 v[92:95], v[132:135], v[180:183], v[92:95]
	v_mfma_f32_16x16x32_bf16 v[84:87], v[152:155], v[176:179], v[84:87]
	v_mfma_f32_16x16x32_bf16 v[84:87], v[156:159], v[180:183], v[84:87]
	v_mfma_f32_16x16x32_bf16 v[68:71], v[128:131], v[184:187], v[68:71]
	v_mfma_f32_16x16x32_bf16 v[68:71], v[132:135], v[200:203], v[68:71]
	v_mfma_f32_16x16x32_bf16 v[64:67], v[152:155], v[184:187], v[64:67]
	v_mfma_f32_16x16x32_bf16 v[64:67], v[156:159], v[200:203], v[64:67]
	s_setprio 0
	s_barrier
	s_add_i32 s36, s38, s75
	s_mov_b32 m0, s36
	ds_read_b128 v[160:163], v240 offset:49152
	ds_read_b128 v[164:167], v240 offset:50176
	ds_read_b128 v[168:171], v240 offset:51200
	ds_read_b128 v[172:175], v240 offset:52224
	ds_read_b128 v[176:179], v240 offset:53248
	ds_read_b128 v[180:183], v240 offset:54272
	ds_read_b128 v[184:187], v240 offset:55296
	ds_read_b128 v[200:203], v240 offset:56320
	s_add_u32 s100, s70, 0x80
	s_addc_u32 s101, s71, 0
	global_load_lds_dwordx4 v188, s[100:101]
	s_add_i32 m0, s36, 0x2000
	s_add_u32 s36, s70, 0x80080
	s_addc_u32 s37, s71, 0
	s_add_i32 s38, s39, s75
	global_load_lds_dwordx4 v194, s[100:101]
	s_mov_b32 m0, s38
	s_nop 0
	global_load_lds_dwordx4 v188, s[36:37]
	s_add_i32 m0, s38, 0x2000
	s_nop 0
	global_load_lds_dwordx4 v194, s[36:37]
	s_mov_b32 m0, s79
	s_nop 0
	s_add_u32 s100, s72, 0x80
	s_addc_u32 s101, s73, 0
	global_load_lds_dwordx4 v188, s[100:101]
	s_mov_b32 m0, s80
	s_nop 0
	global_load_lds_dwordx4 v194, s[100:101]
	s_waitcnt vmcnt(8)
	s_waitcnt lgkmcnt(0)
	s_barrier
	s_setprio 1
	s_waitcnt lgkmcnt(0)
	v_mfma_f32_16x16x32_bf16 v[60:63], v[80:83], v[160:163], v[60:63]
	v_mfma_f32_16x16x32_bf16 v[60:63], v[88:91], v[164:167], v[60:63]
	v_mfma_f32_16x16x32_bf16 v[56:59], v[104:107], v[160:163], v[56:59]
	v_mfma_f32_16x16x32_bf16 v[56:59], v[108:111], v[164:167], v[56:59]
	v_mfma_f32_16x16x32_bf16 v[44:47], v[80:83], v[168:171], v[44:47]
	v_mfma_f32_16x16x32_bf16 v[44:47], v[88:91], v[172:175], v[44:47]
	v_mfma_f32_16x16x32_bf16 v[40:43], v[104:107], v[168:171], v[40:43]
	v_mfma_f32_16x16x32_bf16 v[40:43], v[108:111], v[172:175], v[40:43]
	v_mfma_f32_16x16x32_bf16 v[28:31], v[80:83], v[176:179], v[28:31]
	v_mfma_f32_16x16x32_bf16 v[28:31], v[88:91], v[180:183], v[28:31]
	v_mfma_f32_16x16x32_bf16 v[24:27], v[104:107], v[176:179], v[24:27]
	v_mfma_f32_16x16x32_bf16 v[24:27], v[108:111], v[180:183], v[24:27]
	v_mfma_f32_16x16x32_bf16 v[12:15], v[80:83], v[184:187], v[12:15]
	v_mfma_f32_16x16x32_bf16 v[12:15], v[88:91], v[200:203], v[12:15]
	v_mfma_f32_16x16x32_bf16 v[8:11], v[104:107], v[184:187], v[8:11]
	v_mfma_f32_16x16x32_bf16 v[8:11], v[108:111], v[200:203], v[8:11]
	s_setprio 0
	s_setprio 1
	v_mfma_f32_16x16x32_bf16 v[52:55], v[128:131], v[160:163], v[52:55]
	v_mfma_f32_16x16x32_bf16 v[52:55], v[132:135], v[164:167], v[52:55]
	v_mfma_f32_16x16x32_bf16 v[48:51], v[152:155], v[160:163], v[48:51]
	v_mfma_f32_16x16x32_bf16 v[48:51], v[156:159], v[164:167], v[48:51]
	v_mfma_f32_16x16x32_bf16 v[36:39], v[128:131], v[168:171], v[36:39]
	v_mfma_f32_16x16x32_bf16 v[36:39], v[132:135], v[172:175], v[36:39]
	v_mfma_f32_16x16x32_bf16 v[32:35], v[152:155], v[168:171], v[32:35]
	v_mfma_f32_16x16x32_bf16 v[32:35], v[156:159], v[172:175], v[32:35]
	v_mfma_f32_16x16x32_bf16 v[20:23], v[128:131], v[176:179], v[20:23]
	v_mfma_f32_16x16x32_bf16 v[20:23], v[132:135], v[180:183], v[20:23]
	v_mfma_f32_16x16x32_bf16 v[16:19], v[152:155], v[176:179], v[16:19]
	v_mfma_f32_16x16x32_bf16 v[16:19], v[156:159], v[180:183], v[16:19]
	v_mfma_f32_16x16x32_bf16 v[4:7], v[128:131], v[184:187], v[4:7]
	v_mfma_f32_16x16x32_bf16 v[4:7], v[132:135], v[200:203], v[4:7]
	v_mfma_f32_16x16x32_bf16 v[0:3], v[152:155], v[184:187], v[0:3]
	v_mfma_f32_16x16x32_bf16 v[0:3], v[156:159], v[200:203], v[0:3]
	s_setprio 0
	s_barrier
	s_add_i32 s89, s89, 2
	s_add_u32 s68, s68, 0x100
	s_addc_u32 s69, s69, 0
	s_add_u32 s3, s3, 0x100
	s_addc_u32 s88, s88, 0
	s_cmp_gt_u32 s89, 29

; #define PG8_STAGE(bufoff, gbase, voff) do { _Pragma("unroll") for (int _i = 0; _i < 2; ++_i) \
;         __builtin_amdgcn_global_load_lds((const unsigned*)((const char*)(gbase) + (voff)[_i]), (PG8_LAS unsigned*)(lds + (bufoff) + ldsw + _i * 8192), 16, 0, 0); } while (0)
; #define PG8_LDA(dst, b, h) do { _Pragma("unroll") for (int m = 0; m < 4; ++m) _Pragma("unroll") for (int k = 0; k < 2; ++k) dst[m][k] = *(const PG8_LAS bf16x8*)(lds + PG8_SA(b, h) + aoff + m * 2048 + k * 1024); } while (0)
; #define PG8_LDB(dst, b, h) do { _Pragma("unroll") for (int n = 0; n < 2; ++n) _Pragma("unroll") for (int k = 0; k < 2; ++k) dst[n][k] = *(const PG8_LAS bf16x8*)(lds + PG8_SB(b, h) + boff + n * 2048 + k * 1024); } while (0)
; #define PG8_BAR __builtin_amdgcn_s_barrier()
;     __host__ __device__ bool next(int i, Unit& u) const {
;         const long L = (long)i * G + c; if (L >= nwg) return false;
;         int wgid = (int)L; { const int q = nwg / NXCD, r = nwg % NXCD, xcd = wgid % NXCD, off = wgid / NXCD; wgid = (xcd < r ? xcd * (q + 1) : r * (q + 1) + (xcd - r) * q) + off; }
;         const int nig = WGM * nN, gid = wgid / nig, fm = gid * WGM, gsz = (nM - fm) < WGM ? (nM - fm) : WGM;
;         u.pm = fm + ((wgid % nig) % gsz); u.pn = (wgid % nig) / gsz; return true;
; template <class Epi, class Sched, bool ALIGN_EPI = false, bool SP2 = false>
; __device__ __forceinline__ void gemm_phase(PG8_LAS unsigned char* lds, const Gemm g, const Sched& S, const Epi& E) {
;     ...
;         const bool has_next = S.next(ui + 1, nxt);
;         const char* nA = has_next ? (const char*)g.A + (size_t)nxt.pm * tstep : cA; const char* nB = has_next ? (const char*)g.Bt + (size_t)nxt.pn * tstep : cB;
;         for (int t = 0; t < nt; t += 2) {
;             const bool last = (t == nt - 2);
;             const char* a1 = cA + (size_t)(t + 1) * kstep;
;             const char* a2 = last ? nA : cA + (size_t)(t + 2) * kstep; const char* b2 = last ? nB : cB + (size_t)(t + 2) * kstep;
;             const char* a3 = a2 + kstep; const char* b3 = b2 + kstep;
;             if (last && has_next) S.a_ready(nxt);
;             if constexpr (SP2) {
;             PG8_LDB(B0, 0, 0); PG8_LDB(B1, 0, 1); PG8_SCHED; PG8_LDA(At, 0, 0); PG8_STAGE(PG8_SA(1, 1), a1 + hstep, voffA);
;             PG8_WAIT_V(8); PG8_WAIT_L(0); PG8_BAR; PG8_MMA(0, 0, At, B0); PG8_MMA(0, 1, At, B1); PG8_BAR; PG8_SCHED;
.LBB0_295:
	v_add_u32_e32 v214, 0x10000, v165
	ds_read_b128 v[64:67], v214
	ds_read_b128 v[68:71], v214 offset:1024
	ds_read_b128 v[72:75], v214 offset:2048
	ds_read_b128 v[146:149], v214 offset:3072
	ds_read_b128 v[150:153], v214 offset:16384
	ds_read_b128 v[154:157], v214 offset:17408
	ds_read_b128 v[158:161], v214 offset:18432
	ds_read_b128 v[170:173], v214 offset:19456
	ds_read_b128 v[174:177], v169
	ds_read_b128 v[178:181], v169 offset:1024
	ds_read_b128 v[182:185], v169 offset:2048
	ds_read_b128 v[194:197], v169 offset:3072
	ds_read_b128 v[198:201], v169 offset:4096
	ds_read_b128 v[202:205], v169 offset:5120
	ds_read_b128 v[206:209], v169 offset:6144
	ds_read_b128 v[210:213], v169 offset:7168
	s_add_i32 s54, s54, 1
	s_mul_i32 s3, s54, s55
	s_mul_hi_u32 s12, s54, s86
	s_add_i32 s12, s12, s3
	s_mul_i32 s3, s54, s86
	s_add_u32 s76, s3, s2
	s_addc_u32 s77, s12, s33
	v_mov_b64_e32 v[0:1], s[98:99]
	v_cmp_ge_i64_e32 vcc, s[76:77], v[0:1]
	v_cmp_lt_i64_e64 s[12:13], s[76:77], v[0:1]
	s_cbranch_vccnz .LBB0_297
	s_ashr_i32 s3, s76, 31
	s_lshr_b32 s3, s3, 29
	s_add_i32 s3, s76, s3
	s_ashr_i32 s36, s3, 3
	s_and_b32 s3, s3, -8
	s_sub_i32 s3, s76, s3
	s_lshr_b32 s37, s3, 31
	s_or_b32 s37, s44, s37
	s_mul_i32 s3, s37, s3
	s_add_i32 s3, s3, s36
	s_ashr_i32 s36, s3, 31
	s_lshr_b32 s36, s36, 24
	s_add_i32 s36, s3, s36
	s_ashr_i32 s36, s36, 8
	s_lshl_b32 s37, s36, 3
	s_sub_i32 s38, s45, s37
	s_min_i32 s38, s38, 8
	v_mul_i32_i24_e32 v0, s36, v226
	s_abs_i32 s40, s38
	v_readfirstlane_b32 s36, v0
	v_cvt_f32_u32_e32 v0, s40
	s_sub_i32 s41, 0, s40
	s_sub_i32 s3, s3, s36
	s_abs_i32 s39, s3
	v_rcp_iflag_f32_e32 v0, v0
	s_xor_b32 s36, s3, s38
	s_ashr_i32 s36, s36, 31
	v_mul_f32_e32 v0, 0x4f7ffffe, v0
	v_cvt_u32_f32_e32 v0, v0
	s_nop 0
	v_readfirstlane_b32 s42, v0
	s_mul_i32 s41, s41, s42
	s_mul_hi_u32 s41, s42, s41
	s_add_i32 s42, s42, s41
	s_mul_hi_u32 s41, s39, s42
	s_mul_i32 s42, s41, s40
	s_sub_i32 s39, s39, s42
	s_add_i32 s42, s41, 1
	s_sub_i32 s43, s39, s40
	s_cmp_ge_u32 s39, s40
	s_cselect_b32 s41, s42, s41
	s_cselect_b32 s39, s43, s39
	s_add_i32 s42, s41, 1
	s_cmp_ge_u32 s39, s40
	s_cselect_b32 s39, s42, s41
	s_xor_b32 s39, s39, s36
	s_sub_i32 s74, s39, s36
	s_mul_i32 s36, s74, s38
	s_sub_i32 s3, s3, s36
	s_add_i32 s66, s3, s37
.LBB0_297:
	s_ashr_i32 s67, s66, 31
	s_lshl_b64 s[76:77], s[66:67], 20
	s_add_u32 s78, s34, s76
	s_addc_u32 s79, s35, s77
	s_and_b64 s[76:77], s[12:13], exec
	s_cselect_b32 s65, s79, s69
	s_cselect_b32 s67, s78, s68
	s_ashr_i32 s75, s74, 31
	s_lshl_b64 s[76:77], s[74:75], 20
	s_add_u32 s76, s0, s76
	s_addc_u32 s77, s1, s77
	s_and_b64 s[94:95], s[12:13], exec
	s_cselect_b32 s73, s77, s71
	s_cselect_b32 s75, s76, s70
	s_add_u32 vcc_lo, s68, 0x80080
	s_addc_u32 vcc_hi, s69, 0
	s_add_u32 s3, s70, 0x100
	s_addc_u32 s94, s71, 0
	s_mov_b32 s95, -2
	s_add_u32 s36, vcc_lo, 0xfff80080
	s_addc_u32 s37, vcc_hi, -1
	s_add_i32 s38, 0, 0x10000
	s_cmp_eq_u32 s95, 28
	s_cselect_b32 s71, s65, s37
	s_cselect_b32 s70, s67, s36
	s_cselect_b32 s69, s73, s94
	s_cselect_b32 s68, s75, s3
	s_add_i32 s39, 0, 0x14000
	s_add_i32 m0, s88, 0xc000
	global_load_lds_dwordx4 v142, vcc
	s_add_i32 m0, s88, 0xe000
	s_nop 0
	global_load_lds_dwordx4 v144, vcc
	s_waitcnt lgkmcnt(0)
	s_barrier
	s_setprio 1
	s_waitcnt lgkmcnt(0)
	v_mfma_f32_16x16x32_bf16 v[136:139], v[64:67], v[174:177], 0
	v_mfma_f32_16x16x32_bf16 v[136:139], v[68:71], v[178:181], v[136:139]
	v_mfma_f32_16x16x32_bf16 v[132:135], v[72:75], v[174:177], 0
	v_mfma_f32_16x16x32_bf16 v[132:135], v[146:149], v[178:181], v[132:135]
	v_mfma_f32_16x16x32_bf16 v[120:123], v[64:67], v[182:185], 0
	v_mfma_f32_16x16x32_bf16 v[120:123], v[68:71], v[194:197], v[120:123]
	v_mfma_f32_16x16x32_bf16 v[116:119], v[72:75], v[182:185], 0
	v_mfma_f32_16x16x32_bf16 v[116:119], v[146:149], v[194:197], v[116:119]
	v_mfma_f32_16x16x32_bf16 v[104:107], v[64:67], v[198:201], 0
	v_mfma_f32_16x16x32_bf16 v[104:107], v[68:71], v[202:205], v[104:107]
	v_mfma_f32_16x16x32_bf16 v[100:103], v[72:75], v[198:201], 0
	v_mfma_f32_16x16x32_bf16 v[100:103], v[146:149], v[202:205], v[100:103]
	v_mfma_f32_16x16x32_bf16 v[88:91], v[64:67], v[206:209], 0
	v_mfma_f32_16x16x32_bf16 v[88:91], v[68:71], v[210:213], v[88:91]
	v_mfma_f32_16x16x32_bf16 v[84:87], v[72:75], v[206:209], 0
	v_mfma_f32_16x16x32_bf16 v[84:87], v[146:149], v[210:213], v[84:87]
	s_setprio 0
	s_setprio 1
	v_mfma_f32_16x16x32_bf16 v[128:131], v[150:153], v[174:177], 0
	v_mfma_f32_16x16x32_bf16 v[128:131], v[154:157], v[178:181], v[128:131]
	v_mfma_f32_16x16x32_bf16 v[124:127], v[158:161], v[174:177], 0
	v_mfma_f32_16x16x32_bf16 v[124:127], v[170:173], v[178:181], v[124:127]
	v_mfma_f32_16x16x32_bf16 v[112:115], v[150:153], v[182:185], 0
	v_mfma_f32_16x16x32_bf16 v[112:115], v[154:157], v[194:197], v[112:115]
	v_mfma_f32_16x16x32_bf16 v[108:111], v[158:161], v[182:185], 0
	v_mfma_f32_16x16x32_bf16 v[108:111], v[170:173], v[194:197], v[108:111]
	v_mfma_f32_16x16x32_bf16 v[96:99], v[150:153], v[198:201], 0
	v_mfma_f32_16x16x32_bf16 v[96:99], v[154:157], v[202:205], v[96:99]
	v_mfma_f32_16x16x32_bf16 v[92:95], v[158:161], v[198:201], 0
	v_mfma_f32_16x16x32_bf16 v[92:95], v[170:173], v[202:205], v[92:95]
	v_mfma_f32_16x16x32_bf16 v[80:83], v[150:153], v[206:209], 0
	v_mfma_f32_16x16x32_bf16 v[80:83], v[154:157], v[210:213], v[80:83]
	v_mfma_f32_16x16x32_bf16 v[76:79], v[158:161], v[206:209], 0
	v_mfma_f32_16x16x32_bf16 v[76:79], v[170:173], v[210:213], v[76:79]
	s_setprio 0
	s_barrier
; #define PG8_STAGE(bufoff, gbase, voff) do { _Pragma("unroll") for (int _i = 0; _i < 2; ++_i) \
;         __builtin_amdgcn_global_load_lds((const unsigned*)((const char*)(gbase) + (voff)[_i]), (PG8_LAS unsigned*)(lds + (bufoff) + ldsw + _i * 8192), 16, 0, 0); } while (0)
; #define PG8_LDA(dst, b, h) do { _Pragma("unroll") for (int m = 0; m < 4; ++m) _Pragma("unroll") for (int k = 0; k < 2; ++k) dst[m][k] = *(const PG8_LAS bf16x8*)(lds + PG8_SA(b, h) + aoff + m * 2048 + k * 1024); } while (0)
; #define PG8_LDB(dst, b, h) do { _Pragma("unroll") for (int n = 0; n < 2; ++n) _Pragma("unroll") for (int k = 0; k < 2; ++k) dst[n][k] = *(const PG8_LAS bf16x8*)(lds + PG8_SB(b, h) + boff + n * 2048 + k * 1024); } while (0)
; #define PG8_MMA(ai, bj, At, Bt) do { __builtin_amdgcn_s_setprio(1); _Pragma("unroll") for (int m = 0; m < 4; ++m) _Pragma("unroll") for (int n = 0; n < 2; ++n) _Pragma("unroll") for (int k = 0; k < 2; ++k) \
;         acc[ai][bj][m][n] = __builtin_amdgcn_mfma_f32_16x16x32_bf16(Bt[n][k], At[m][k], acc[ai][bj][m][n], 0, 0, 0); __builtin_amdgcn_s_setprio(0); } while (0)
; #define PG8_WAIT_V(n) asm volatile("s_waitcnt vmcnt(" #n ")" ::: "memory")
; #define PG8_WAIT_L(n) asm volatile("s_waitcnt lgkmcnt(" #n ")" ::: "memory")
; #define PG8_BAR __builtin_amdgcn_s_barrier()
; #define PG8_SCHED __builtin_amdgcn_sched_barrier(0)
; template <class Epi, class Sched, bool ALIGN_EPI = false, bool SP2 = false>
; __device__ __forceinline__ void gemm_phase(PG8_LAS unsigned char* lds, const Gemm g, const Sched& S, const Epi& E) {
;     ...
;             PG8_LDA(At, 0, 1); PG8_STAGE(PG8_SB(0, 0), b2, voffB); PG8_STAGE(PG8_SB(0, 1), b2 + hstep, voffB); PG8_STAGE(PG8_SA(0, 0), a2, voffA);
;             PG8_WAIT_V(8); PG8_WAIT_L(0); PG8_BAR; PG8_MMA(1, 0, At, B0); PG8_MMA(1, 1, At, B1); PG8_BAR; PG8_SCHED;
;             PG8_LDB(B0, 1, 0); PG8_LDB(B1, 1, 1); PG8_SCHED; PG8_LDA(At, 1, 0); PG8_STAGE(PG8_SA(0, 1), a2 + hstep, voffA);
;             PG8_WAIT_V(8); PG8_WAIT_L(0); PG8_BAR; PG8_MMA(0, 0, At, B0); PG8_MMA(0, 1, At, B1); PG8_BAR; PG8_SCHED;
	s_add_i32 s36, s38, s87
	s_mov_b32 m0, s36
	ds_read_b128 v[174:177], v169 offset:16384
	ds_read_b128 v[178:181], v169 offset:17408
	ds_read_b128 v[182:185], v169 offset:18432
	ds_read_b128 v[194:197], v169 offset:19456
	ds_read_b128 v[198:201], v169 offset:20480
	ds_read_b128 v[202:205], v169 offset:21504
	ds_read_b128 v[206:209], v169 offset:22528
	ds_read_b128 v[210:213], v169 offset:23552
	global_load_lds_dwordx4 v188, s[68:69]
	s_add_i32 m0, s36, 0x2000
	s_add_u32 s36, s68, 0x80000
	s_addc_u32 s37, s69, 0
	s_add_i32 s38, s39, s87
	global_load_lds_dwordx4 v140, s[68:69]
	s_mov_b32 m0, s38
	s_nop 0
	global_load_lds_dwordx4 v188, s[36:37]
	s_add_i32 m0, s38, 0x2000
	s_nop 0
	global_load_lds_dwordx4 v140, s[36:37]
	s_mov_b32 m0, s88
	s_nop 0
	global_load_lds_dwordx4 v188, s[70:71]
	s_mov_b32 m0, s89
	s_nop 0
	global_load_lds_dwordx4 v140, s[70:71]
	s_waitcnt lgkmcnt(0)
	s_barrier
	s_setprio 1
	s_waitcnt lgkmcnt(0)
	v_mfma_f32_16x16x32_bf16 v[56:59], v[64:67], v[174:177], 0
	v_mfma_f32_16x16x32_bf16 v[56:59], v[68:71], v[178:181], v[56:59]
	v_mfma_f32_16x16x32_bf16 v[60:63], v[72:75], v[174:177], 0
	v_mfma_f32_16x16x32_bf16 v[60:63], v[146:149], v[178:181], v[60:63]
	v_mfma_f32_16x16x32_bf16 v[40:43], v[64:67], v[182:185], 0
	v_mfma_f32_16x16x32_bf16 v[40:43], v[68:71], v[194:197], v[40:43]
	v_mfma_f32_16x16x32_bf16 v[44:47], v[72:75], v[182:185], 0
	v_mfma_f32_16x16x32_bf16 v[44:47], v[146:149], v[194:197], v[44:47]
	v_mfma_f32_16x16x32_bf16 v[24:27], v[64:67], v[198:201], 0
	v_mfma_f32_16x16x32_bf16 v[24:27], v[68:71], v[202:205], v[24:27]
	v_mfma_f32_16x16x32_bf16 v[28:31], v[72:75], v[198:201], 0
	v_mfma_f32_16x16x32_bf16 v[28:31], v[146:149], v[202:205], v[28:31]
	v_mfma_f32_16x16x32_bf16 v[8:11], v[64:67], v[206:209], 0
	v_mfma_f32_16x16x32_bf16 v[8:11], v[68:71], v[210:213], v[8:11]
	v_mfma_f32_16x16x32_bf16 v[12:15], v[72:75], v[206:209], 0
	v_mfma_f32_16x16x32_bf16 v[12:15], v[146:149], v[210:213], v[12:15]
	s_setprio 0
	s_setprio 1
	v_mfma_f32_16x16x32_bf16 v[52:55], v[150:153], v[174:177], 0
	v_mfma_f32_16x16x32_bf16 v[52:55], v[154:157], v[178:181], v[52:55]
	v_mfma_f32_16x16x32_bf16 v[48:51], v[158:161], v[174:177], 0
	v_mfma_f32_16x16x32_bf16 v[48:51], v[170:173], v[178:181], v[48:51]
	v_mfma_f32_16x16x32_bf16 v[36:39], v[150:153], v[182:185], 0
	v_mfma_f32_16x16x32_bf16 v[36:39], v[154:157], v[194:197], v[36:39]
	v_mfma_f32_16x16x32_bf16 v[32:35], v[158:161], v[182:185], 0
	v_mfma_f32_16x16x32_bf16 v[32:35], v[170:173], v[194:197], v[32:35]
	v_mfma_f32_16x16x32_bf16 v[20:23], v[150:153], v[198:201], 0
	v_mfma_f32_16x16x32_bf16 v[20:23], v[154:157], v[202:205], v[20:23]
	v_mfma_f32_16x16x32_bf16 v[16:19], v[158:161], v[198:201], 0
	v_mfma_f32_16x16x32_bf16 v[16:19], v[170:173], v[202:205], v[16:19]
	v_mfma_f32_16x16x32_bf16 v[4:7], v[150:153], v[206:209], 0
	v_mfma_f32_16x16x32_bf16 v[4:7], v[154:157], v[210:213], v[4:7]
	v_mfma_f32_16x16x32_bf16 v[0:3], v[158:161], v[206:209], 0
	v_mfma_f32_16x16x32_bf16 v[0:3], v[170:173], v[210:213], v[0:3]
	s_setprio 0
	s_barrier
	s_add_i32 s38, 0, 0x18000
	s_add_i32 s39, 0, 0x1c000
	ds_read_b128 v[64:67], v214 offset:32768
	ds_read_b128 v[68:71], v214 offset:33792
	ds_read_b128 v[72:75], v214 offset:34816
	ds_read_b128 v[146:149], v214 offset:35840
	ds_read_b128 v[150:153], v214 offset:49152
	ds_read_b128 v[154:157], v214 offset:50176
	ds_read_b128 v[158:161], v214 offset:51200
	ds_read_b128 v[170:173], v214 offset:52224
	s_add_u32 s36, s70, 0x80000
	s_addc_u32 s37, s71, 0
	s_mov_b32 m0, s14
	ds_read_b128 v[174:177], v169 offset:32768
	ds_read_b128 v[178:181], v169 offset:33792
	ds_read_b128 v[182:185], v169 offset:34816
	ds_read_b128 v[194:197], v169 offset:35840
	ds_read_b128 v[198:201], v169 offset:36864
	ds_read_b128 v[202:205], v169 offset:37888
	ds_read_b128 v[206:209], v169 offset:38912
	ds_read_b128 v[210:213], v169 offset:39936
	global_load_lds_dwordx4 v188, s[36:37]
	s_mov_b32 m0, s15
	s_nop 0
	global_load_lds_dwordx4 v140, s[36:37]
	s_waitcnt vmcnt(8)
	s_waitcnt lgkmcnt(0)
	s_barrier
; #define PG8_STAGE(bufoff, gbase, voff) do { _Pragma("unroll") for (int _i = 0; _i < 2; ++_i) \
;         __builtin_amdgcn_global_load_lds((const unsigned*)((const char*)(gbase) + (voff)[_i]), (PG8_LAS unsigned*)(lds + (bufoff) + ldsw + _i * 8192), 16, 0, 0); } while (0)
; #define PG8_LDA(dst, b, h) do { _Pragma("unroll") for (int m = 0; m < 4; ++m) _Pragma("unroll") for (int k = 0; k < 2; ++k) dst[m][k] = *(const PG8_LAS bf16x8*)(lds + PG8_SA(b, h) + aoff + m * 2048 + k * 1024); } while (0)
; #define PG8_MMA(ai, bj, At, Bt) do { __builtin_amdgcn_s_setprio(1); _Pragma("unroll") for (int m = 0; m < 4; ++m) _Pragma("unroll") for (int n = 0; n < 2; ++n) _Pragma("unroll") for (int k = 0; k < 2; ++k) \
;         acc[ai][bj][m][n] = __builtin_amdgcn_mfma_f32_16x16x32_bf16(Bt[n][k], At[m][k], acc[ai][bj][m][n], 0, 0, 0); __builtin_amdgcn_s_setprio(0); } while (0)
; #define PG8_WAIT_V(n) asm volatile("s_waitcnt vmcnt(" #n ")" ::: "memory")
; #define PG8_WAIT_L(n) asm volatile("s_waitcnt lgkmcnt(" #n ")" ::: "memory")
; #define PG8_BAR __builtin_amdgcn_s_barrier()
; #define PG8_SCHED __builtin_amdgcn_sched_barrier(0)
; template <class Epi, class Sched, bool ALIGN_EPI = false, bool SP2 = false>
; __device__ __forceinline__ void gemm_phase(PG8_LAS unsigned char* lds, const Gemm g, const Sched& S, const Epi& E) {
;     ...
;             PG8_WAIT_V(8); PG8_WAIT_L(0); PG8_BAR; PG8_MMA(0, 0, At, B0); PG8_MMA(0, 1, At, B1); PG8_BAR; PG8_SCHED;
;             PG8_LDA(At, 1, 1); PG8_STAGE(PG8_SB(1, 0), b3, voffB); PG8_STAGE(PG8_SB(1, 1), b3 + hstep, voffB); PG8_STAGE(PG8_SA(1, 0), a3, voffA);
;             PG8_WAIT_V(8); PG8_WAIT_L(0); PG8_BAR; PG8_MMA(1, 0, At, B0); PG8_MMA(1, 1, At, B1); PG8_BAR; PG8_SCHED;
	s_setprio 1
	s_waitcnt lgkmcnt(0)
	v_mfma_f32_16x16x32_bf16 v[136:139], v[64:67], v[174:177], v[136:139]
	v_mfma_f32_16x16x32_bf16 v[136:139], v[68:71], v[178:181], v[136:139]
	v_mfma_f32_16x16x32_bf16 v[132:135], v[72:75], v[174:177], v[132:135]
	v_mfma_f32_16x16x32_bf16 v[132:135], v[146:149], v[178:181], v[132:135]
	v_mfma_f32_16x16x32_bf16 v[120:123], v[64:67], v[182:185], v[120:123]
	v_mfma_f32_16x16x32_bf16 v[120:123], v[68:71], v[194:197], v[120:123]
	v_mfma_f32_16x16x32_bf16 v[116:119], v[72:75], v[182:185], v[116:119]
	v_mfma_f32_16x16x32_bf16 v[116:119], v[146:149], v[194:197], v[116:119]
	v_mfma_f32_16x16x32_bf16 v[104:107], v[64:67], v[198:201], v[104:107]
	v_mfma_f32_16x16x32_bf16 v[104:107], v[68:71], v[202:205], v[104:107]
	v_mfma_f32_16x16x32_bf16 v[100:103], v[72:75], v[198:201], v[100:103]
	v_mfma_f32_16x16x32_bf16 v[100:103], v[146:149], v[202:205], v[100:103]
	v_mfma_f32_16x16x32_bf16 v[88:91], v[64:67], v[206:209], v[88:91]
	v_mfma_f32_16x16x32_bf16 v[88:91], v[68:71], v[210:213], v[88:91]
	v_mfma_f32_16x16x32_bf16 v[84:87], v[72:75], v[206:209], v[84:87]
	v_mfma_f32_16x16x32_bf16 v[84:87], v[146:149], v[210:213], v[84:87]
	s_setprio 0
	s_setprio 1
	v_mfma_f32_16x16x32_bf16 v[128:131], v[150:153], v[174:177], v[128:131]
	v_mfma_f32_16x16x32_bf16 v[128:131], v[154:157], v[178:181], v[128:131]
	v_mfma_f32_16x16x32_bf16 v[124:127], v[158:161], v[174:177], v[124:127]
	v_mfma_f32_16x16x32_bf16 v[124:127], v[170:173], v[178:181], v[124:127]
	v_mfma_f32_16x16x32_bf16 v[112:115], v[150:153], v[182:185], v[112:115]
	v_mfma_f32_16x16x32_bf16 v[112:115], v[154:157], v[194:197], v[112:115]
	v_mfma_f32_16x16x32_bf16 v[108:111], v[158:161], v[182:185], v[108:111]
	v_mfma_f32_16x16x32_bf16 v[108:111], v[170:173], v[194:197], v[108:111]
	v_mfma_f32_16x16x32_bf16 v[96:99], v[150:153], v[198:201], v[96:99]
	v_mfma_f32_16x16x32_bf16 v[96:99], v[154:157], v[202:205], v[96:99]
	v_mfma_f32_16x16x32_bf16 v[92:95], v[158:161], v[198:201], v[92:95]
	v_mfma_f32_16x16x32_bf16 v[92:95], v[170:173], v[202:205], v[92:95]
	v_mfma_f32_16x16x32_bf16 v[80:83], v[150:153], v[206:209], v[80:83]
	v_mfma_f32_16x16x32_bf16 v[80:83], v[154:157], v[210:213], v[80:83]
	v_mfma_f32_16x16x32_bf16 v[76:79], v[158:161], v[206:209], v[76:79]
	v_mfma_f32_16x16x32_bf16 v[76:79], v[170:173], v[210:213], v[76:79]
	s_setprio 0
	s_barrier
	s_add_i32 s36, s38, s87
	s_mov_b32 m0, s36
	ds_read_b128 v[174:177], v169 offset:49152
	ds_read_b128 v[178:181], v169 offset:50176
	ds_read_b128 v[182:185], v169 offset:51200
	ds_read_b128 v[194:197], v169 offset:52224
	ds_read_b128 v[198:201], v169 offset:53248
	ds_read_b128 v[202:205], v169 offset:54272
	ds_read_b128 v[206:209], v169 offset:55296
	ds_read_b128 v[210:213], v169 offset:56320
	s_add_u32 s100, s68, 0x80
	s_addc_u32 s101, s69, 0
	global_load_lds_dwordx4 v188, s[100:101]
	s_add_i32 m0, s36, 0x2000
	s_add_u32 s36, s68, 0x80080
	s_addc_u32 s37, s69, 0
	s_add_i32 s38, s39, s87
	global_load_lds_dwordx4 v140, s[100:101]
	s_mov_b32 m0, s38
	s_nop 0
	global_load_lds_dwordx4 v188, s[36:37]
	s_add_i32 m0, s38, 0x2000
	s_nop 0
	global_load_lds_dwordx4 v140, s[36:37]
	s_mov_b32 m0, s81
	s_nop 0
	s_add_u32 s100, s70, 0x80
	s_addc_u32 s101, s71, 0
	global_load_lds_dwordx4 v188, s[100:101]
	s_mov_b32 m0, s80
	s_nop 0
	global_load_lds_dwordx4 v140, s[100:101]
	s_waitcnt vmcnt(8)
	s_waitcnt lgkmcnt(0)
	s_barrier
	s_setprio 1
	s_waitcnt lgkmcnt(0)
	v_mfma_f32_16x16x32_bf16 v[56:59], v[64:67], v[174:177], v[56:59]
	v_mfma_f32_16x16x32_bf16 v[56:59], v[68:71], v[178:181], v[56:59]
	v_mfma_f32_16x16x32_bf16 v[60:63], v[72:75], v[174:177], v[60:63]
	v_mfma_f32_16x16x32_bf16 v[60:63], v[146:149], v[178:181], v[60:63]
	v_mfma_f32_16x16x32_bf16 v[40:43], v[64:67], v[182:185], v[40:43]
	v_mfma_f32_16x16x32_bf16 v[40:43], v[68:71], v[194:197], v[40:43]
	v_mfma_f32_16x16x32_bf16 v[44:47], v[72:75], v[182:185], v[44:47]
	v_mfma_f32_16x16x32_bf16 v[44:47], v[146:149], v[194:197], v[44:47]
	v_mfma_f32_16x16x32_bf16 v[24:27], v[64:67], v[198:201], v[24:27]
	v_mfma_f32_16x16x32_bf16 v[24:27], v[68:71], v[202:205], v[24:27]
	v_mfma_f32_16x16x32_bf16 v[28:31], v[72:75], v[198:201], v[28:31]
	v_mfma_f32_16x16x32_bf16 v[28:31], v[146:149], v[202:205], v[28:31]
	v_mfma_f32_16x16x32_bf16 v[8:11], v[64:67], v[206:209], v[8:11]
	v_mfma_f32_16x16x32_bf16 v[8:11], v[68:71], v[210:213], v[8:11]
	v_mfma_f32_16x16x32_bf16 v[12:15], v[72:75], v[206:209], v[12:15]
	v_mfma_f32_16x16x32_bf16 v[12:15], v[146:149], v[210:213], v[12:15]
	s_setprio 0
	s_setprio 1
	v_mfma_f32_16x16x32_bf16 v[52:55], v[150:153], v[174:177], v[52:55]
	v_mfma_f32_16x16x32_bf16 v[52:55], v[154:157], v[178:181], v[52:55]
	v_mfma_f32_16x16x32_bf16 v[48:51], v[158:161], v[174:177], v[48:51]
	v_mfma_f32_16x16x32_bf16 v[48:51], v[170:173], v[178:181], v[48:51]
	v_mfma_f32_16x16x32_bf16 v[36:39], v[150:153], v[182:185], v[36:39]
	v_mfma_f32_16x16x32_bf16 v[36:39], v[154:157], v[194:197], v[36:39]
	v_mfma_f32_16x16x32_bf16 v[32:35], v[158:161], v[182:185], v[32:35]
	v_mfma_f32_16x16x32_bf16 v[32:35], v[170:173], v[194:197], v[32:35]
	v_mfma_f32_16x16x32_bf16 v[20:23], v[150:153], v[198:201], v[20:23]
	v_mfma_f32_16x16x32_bf16 v[20:23], v[154:157], v[202:205], v[20:23]
	v_mfma_f32_16x16x32_bf16 v[16:19], v[158:161], v[198:201], v[16:19]
	v_mfma_f32_16x16x32_bf16 v[16:19], v[170:173], v[202:205], v[16:19]
	v_mfma_f32_16x16x32_bf16 v[4:7], v[150:153], v[206:209], v[4:7]
	v_mfma_f32_16x16x32_bf16 v[4:7], v[154:157], v[210:213], v[4:7]
	v_mfma_f32_16x16x32_bf16 v[0:3], v[158:161], v[206:209], v[0:3]
	v_mfma_f32_16x16x32_bf16 v[0:3], v[170:173], v[210:213], v[0:3]
	s_setprio 0
	s_barrier
	s_add_i32 s95, s95, 2
	s_add_u32 vcc_lo, vcc_lo, 0x100
	s_addc_u32 vcc_hi, vcc_hi, 0
	s_add_u32 s3, s3, 0x100
	s_addc_u32 s94, s94, 0
	s_cmp_gt_u32 s95, 29

; __device__ __forceinline__ float silu_f(float x) { return x * __builtin_amdgcn_rcpf(1.f + __expf(-x)); }
;     __device__ __forceinline__ void operator()(const f32x4 (&acc)[2][2][4][2], const Unit& u, int wr, int wc, int fr, int fq) const {
;     ...
;         for (int ai = 0; ai < 2; ++ai)
; #pragma unroll
;             for (int m = 0; m < 4; ++m) rstd[ai][m] = (float)ss[r0 + ai * HALF + m * 16] * (1.f / 16777216.f);
;         const f32x4 w0 = *(const f32x4*)(cw + ch), w1 = *(const f32x4*)(cw + 2048 + ch), w2 = *(const f32x4*)(cw + 4096 + ch);
;         const bool fuse = u.pm != 96;
;         const int lr = (lane & 48) | ((fr + 15) & 15), ll = (lane & 48) | ((fr + 1) & 15);
; #pragma unroll
;         for (int ai = 0; ai < 2; ++ai) {
;             f32x4 g[4], cu[4];
; #pragma unroll
;             for (int m = 0; m < 4; ++m) {
;                 const float rs = __builtin_amdgcn_rsqf(rstd[ai][m] * (1.f / 2048.f) + 1e-6f);
;                 const f32x4 b = acc[ai][0][m][0] * rs, z = acc[ai][0][m][1] * rs, c = acc[ai][1][m][0] * rs, uu = acc[ai][1][m][1] * rs;
; #pragma unroll
;                 for (int j = 0; j < 4; ++j) { g[m][j] = b[j] * silu_f(z[j]); cu[m][j] = c[j] * uu[j]; }
;             }
.LBB0_311:
	s_or_b64 exec, exec, s[68:69]
	v_ffbh_u32_e32 v76, v163
	v_min_u32_e32 v78, 32, v76
	v_lshlrev_b64 v[76:77], v78, v[162:163]
	v_min_u32_e32 v76, 1, v76
	v_or_b32_e32 v76, v77, v76
	v_cvt_f32_u32_e32 v76, v76
	v_sub_u32_e32 v77, 32, v78
	v_add_u32_e32 v82, 0x80, v148
	v_ashrrev_i32_e32 v83, 31, v82
	v_ldexp_f32 v76, v76, v77
	v_mul_f32_e32 v86, 0x33800000, v76
	v_ffbh_u32_e32 v76, v159
	v_min_u32_e32 v78, 32, v76
	v_lshlrev_b64 v[76:77], v78, v[158:159]
	v_min_u32_e32 v76, 1, v76
	v_or_b32_e32 v76, v77, v76
	v_cvt_f32_u32_e32 v76, v76
	v_sub_u32_e32 v77, 32, v78
	v_add_u32_e32 v80, 0x90, v148
	v_ldexp_f32 v76, v76, v77
	v_mul_f32_e32 v87, 0x33800000, v76
	v_ffbh_u32_e32 v76, v157
	v_min_u32_e32 v84, 32, v76
	v_lshlrev_b64 v[76:77], v84, v[156:157]
	v_min_u32_e32 v76, 1, v76
	v_or_b32_e32 v76, v77, v76
	v_cvt_f32_u32_e32 v76, v76
	v_sub_u32_e32 v77, 32, v84
	v_add_u32_e32 v78, 0xa0, v148
	v_ashrrev_i32_e32 v81, 31, v80
	v_ldexp_f32 v76, v76, v77
	v_ffbh_u32_e32 v77, v153
	v_min_u32_e32 v89, 32, v77
	v_fmamk_f32 v77, v86, 0x3a000000, v227
	v_rsq_f32_e32 v86, v77
	v_lshlrev_b64 v[84:85], v89, v[152:153]
	v_min_u32_e32 v77, 1, v84
	v_or_b32_e32 v77, v85, v77
	v_mul_f32_e32 v60, v60, v86
	v_cvt_f32_u32_e32 v84, v77
	v_mul_f32_e32 v77, 0xbfb8aa3b, v60
	v_exp_f32_e32 v85, v77
	v_mul_f32_e32 v56, v56, v86
	v_mul_f32_e32 v52, v52, v86
	v_mul_f32_e32 v48, v48, v86
	v_add_f32_e32 v85, 1.0, v85
	v_rcp_f32_e32 v85, v85
	v_mul_f32_e32 v48, v52, v48
	v_mul_f32_e32 v52, v57, v86
	v_mul_f32_e32 v53, v53, v86
	v_mul_f32_e32 v60, v60, v85
	v_mul_f32_e32 v56, v56, v60
	v_mul_f32_e32 v60, v61, v86
	v_mul_f32_e32 v61, 0xbfb8aa3b, v60
	v_exp_f32_e32 v61, v61
	v_mul_f32_e32 v49, v49, v86
	v_mul_f32_e32 v49, v53, v49
	v_mul_f32_e32 v53, v58, v86
	v_add_f32_e32 v57, 1.0, v61
	v_mul_f32_e32 v61, v62, v86
	v_rcp_f32_e32 v57, v57
	v_mul_f32_e32 v62, 0xbfb8aa3b, v61
	v_exp_f32_e32 v62, v62
	v_mul_f32_e32 v54, v54, v86
	v_mul_f32_e32 v57, v60, v57
	v_mul_f32_e32 v52, v52, v57
	v_add_f32_e32 v57, 1.0, v62
	v_rcp_f32_e32 v57, v57
	v_mul_f32_e32 v50, v50, v86
	v_fmamk_f32 v58, v87, 0x3a000000, v227
	v_mul_f32_e32 v50, v54, v50
	v_mul_f32_e32 v57, v61, v57
	v_mul_f32_e32 v54, v63, v86
	v_rsq_f32_e32 v58, v58
	v_mul_f32_e32 v53, v53, v57
	v_mul_f32_e32 v57, 0xbfb8aa3b, v54
	v_exp_f32_e32 v57, v57
	v_mul_f32_e32 v60, v44, v58
	v_mul_f32_e32 v44, 0xbfb8aa3b, v60
	v_exp_f32_e32 v44, v44
	v_add_f32_e32 v57, 1.0, v57
	v_rcp_f32_e32 v57, v57
	v_mul_f32_e32 v40, v40, v58
	v_add_f32_e32 v44, 1.0, v44
	v_mul_f32_e32 v45, v45, v58
	v_mul_f32_e32 v54, v54, v57
	v_rcp_f32_e32 v57, v44
	v_mul_f32_e32 v44, v51, v86
	v_mul_f32_e32 v36, v36, v58
	v_mul_f32_e32 v32, v32, v58
	v_mul_f32_e32 v51, v60, v57
	v_mul_f32_e32 v40, v40, v51
	v_mul_f32_e32 v51, 0xbfb8aa3b, v45
	v_exp_f32_e32 v51, v51
	v_mul_f32_e32 v32, v36, v32
	v_mul_f32_e32 v36, v41, v58
	v_mul_f32_e32 v46, v46, v58
	v_add_f32_e32 v41, 1.0, v51
	v_rcp_f32_e32 v41, v41
	v_mul_f32_e32 v51, 0xbfb8aa3b, v46
	v_exp_f32_e32 v51, v51
	v_mul_f32_e32 v88, 0x33800000, v76
	v_mul_f32_e32 v41, v45, v41
	v_mul_f32_e32 v36, v36, v41
	v_add_f32_e32 v41, 1.0, v51
	v_rcp_f32_e32 v41, v41
	v_mul_f32_e32 v37, v37, v58
	v_mul_f32_e32 v33, v33, v58
	v_mul_f32_e32 v38, v38, v58
	v_mul_f32_e32 v34, v34, v58
	v_mul_f32_e32 v33, v37, v33
	v_mul_f32_e32 v37, v42, v58
	v_mul_f32_e32 v41, v46, v41
	v_mul_f32_e32 v34, v38, v34
	v_mul_f32_e32 v38, v47, v58
	v_fmamk_f32 v42, v88, 0x3a000000, v227
	v_mul_f32_e32 v37, v37, v41
	v_mul_f32_e32 v41, 0xbfb8aa3b, v38
	v_rsq_f32_e32 v42, v42
	v_exp_f32_e32 v41, v41
	v_mul_f32_e32 v39, v39, v58
	v_mul_f32_e32 v35, v35, v58
	v_mul_f32_e32 v28, v28, v42
	v_add_f32_e32 v41, 1.0, v41
	v_mul_f32_e32 v45, 0xbfb8aa3b, v28
	v_rcp_f32_e32 v41, v41
	v_exp_f32_e32 v45, v45
	v_mul_f32_e32 v24, v24, v42
	v_mul_f32_e32 v29, v29, v42
	v_mul_f32_e32 v38, v38, v41
	v_add_f32_e32 v41, 1.0, v45
	v_rcp_f32_e32 v41, v41
	v_mul_f32_e32 v35, v39, v35
	v_mul_f32_e32 v20, v20, v42
	v_mul_f32_e32 v16, v16, v42
	v_mul_f32_e32 v28, v28, v41
	v_mul_f32_e32 v24, v24, v28
	v_mul_f32_e32 v28, 0xbfb8aa3b, v29
	v_exp_f32_e32 v39, v28
	v_mul_f32_e32 v28, v20, v16
	v_mul_f32_e32 v30, v30, v42
	v_mul_f32_e32 v16, v25, v42
	v_add_f32_e32 v20, 1.0, v39
	v_rcp_f32_e32 v20, v20
	v_mul_f32_e32 v25, 0xbfb8aa3b, v30
	v_exp_f32_e32 v25, v25
	v_mul_f32_e32 v17, v17, v42
	v_mul_f32_e32 v20, v29, v20
	v_mul_f32_e32 v29, v16, v20
	v_add_f32_e32 v20, 1.0, v25
	v_rcp_f32_e32 v20, v20
	v_mul_f32_e32 v16, v21, v42
	v_mul_f32_e32 v25, v16, v17
	v_mul_f32_e32 v16, v26, v42
	v_mul_f32_e32 v17, v30, v20
	v_mul_f32_e32 v26, v16, v17
	v_mul_f32_e32 v16, v31, v42
	v_mul_f32_e32 v17, 0xbfb8aa3b, v16
	v_sub_u32_e32 v89, 32, v89
	v_exp_f32_e32 v17, v17
	v_ldexp_f32 v84, v84, v89
	v_mul_f32_e32 v84, 0x33800000, v84
	v_mul_f32_e32 v20, v22, v42
	v_mul_f32_e32 v18, v18, v42
	v_mul_f32_e32 v22, v20, v18
	v_fmamk_f32 v20, v84, 0x3a000000, v227
	v_add_f32_e32 v17, 1.0, v17
	v_rsq_f32_e32 v20, v20
	v_rcp_f32_e32 v17, v17
	v_mul_f32_e32 v18, v27, v42
	v_add_u32_e32 v76, 0xb0, v148
	v_mul_f32_e32 v12, v12, v20
	v_mul_f32_e32 v16, v16, v17
	v_mul_f32_e32 v17, 0xbfb8aa3b, v12
	v_exp_f32_e32 v17, v17
	v_mul_f32_e32 v27, v18, v16
	v_mul_f32_e32 v16, v23, v42
	v_mul_f32_e32 v18, v19, v42
	v_mul_f32_e32 v23, v16, v18
	v_add_f32_e32 v16, 1.0, v17
	v_mul_f32_e32 v17, v13, v20
	v_rcp_f32_e32 v16, v16
	v_mul_f32_e32 v13, 0xbfb8aa3b, v17
	v_exp_f32_e32 v13, v13
	v_mul_f32_e32 v8, v8, v20
	v_mul_f32_e32 v12, v12, v16
	v_mul_f32_e32 v30, v8, v12
	v_add_f32_e32 v8, 1.0, v13
	v_rcp_f32_e32 v8, v8
	v_mul_f32_e32 v4, v4, v20
	v_mul_f32_e32 v0, v0, v20
	v_mul_f32_e32 v13, v4, v0
	v_mul_f32_e32 v0, v9, v20
	v_mul_f32_e32 v4, v17, v8
	v_mul_f32_e32 v31, v0, v4
	v_mul_f32_e32 v4, v14, v20
	v_mul_f32_e32 v0, v5, v20
	v_mul_f32_e32 v5, 0xbfb8aa3b, v4
	v_exp_f32_e32 v5, v5
	v_mul_f32_e32 v8, v15, v20
	v_mul_f32_e32 v9, 0xbfb8aa3b, v8
	v_exp_f32_e32 v9, v9
	v_add_f32_e32 v5, 1.0, v5
	v_rcp_f32_e32 v5, v5
	v_mul_f32_e32 v1, v1, v20
	v_mul_f32_e32 v1, v0, v1
	v_mul_f32_e32 v0, v10, v20
	v_mul_f32_e32 v4, v4, v5
	v_mul_f32_e32 v39, v0, v4
	v_add_f32_e32 v4, 1.0, v9
	v_rcp_f32_e32 v4, v4
	v_mul_f32_e32 v0, v6, v20
	v_mul_f32_e32 v2, v2, v20
	v_mul_f32_e32 v5, v0, v2
	v_mul_f32_e32 v0, v11, v20
	v_mul_f32_e32 v2, v8, v4
	v_mul_f32_e32 v59, v59, v86
	v_mul_f32_e32 v55, v55, v86
	v_mul_f32_e32 v43, v43, v58
	v_mul_f32_e32 v41, v0, v2
	v_mul_f32_e32 v0, v7, v20
	v_mul_f32_e32 v2, v3, v20
	v_lshlrev_b64 v[6:7], 11, v[82:83]
	v_ashrrev_i32_e32 v79, 31, v78
	v_ashrrev_i32_e32 v77, 31, v76
	v_mul_f32_e32 v54, v59, v54
	v_mul_f32_e32 v44, v55, v44
	v_mul_f32_e32 v38, v43, v38
	v_mul_f32_e32 v3, v0, v2
	s_andn2_b64 vcc, exec, s[72:73]
	v_lshl_add_u64 v[6:7], v[6:7], 0, v[146:147]
	s_cbranch_vccnz .LBB0_317
; __device__ __forceinline__ unsigned cvt_pk_bf16(float lo, float hi) { unsigned r; asm volatile("v_cvt_pk_bf16_f32 %0, %1, %2" : "=v"(r) : "v"(lo), "v"(hi)); return r; }
;     __device__ __forceinline__ void operator()(const f32x4 (&acc)[2][2][4][2], const Unit& u, int wr, int wc, int fr, int fq) const {
;     ...
;             if (fuse) {
;                 f32x4 R[4], L[4];
; #pragma unroll
;                 for (int m = 0; m < 4; ++m)
; #pragma unroll
;                     for (int j = 0; j < 4; ++j) { R[m][j] = __shfl(cu[m][j], lr); L[m][j] = __shfl(cu[m][j], ll); }
; #pragma unroll
;                 for (int m = 0; m < 4; ++m) {
;                     const int r = r0 + ai * HALF + m * 16;
;                     const f32x4 prev = (fr == 0) ? R[m > 0 ? m - 1 : 0] : R[m], next = (fr == 15) ? L[m < 3 ? m + 1 : 3] : L[m];
;                     const bool edge = (m == 0 && fr == 0) || (m == 3 && fr == 15);
;                     f32x4 y;
; #pragma unroll
;                     for (int j = 0; j < 4; ++j) { const float t = g[m][j] * (prev[j] * w0[j] + cu[m][j] * w1[j] + next[j] * w2[j]); y[j] = edge ? g[m][j] : t; }
;                     const size_t off = (size_t)r * 2048 + ch;
;                     u32x2 o1; o1.x = cvt_pk_bf16(y[0], y[1]); o1.y = cvt_pk_bf16(y[2], y[3]);
;                     *(u32x2*)(G + off) = o1;
;                     if ((m == 0 && fr <= 1) || (m == 3 && fr >= 14)) { u32x2 o2; o2.x = cvt_pk_bf16(cu[m][0], cu[m][1]); o2.y = cvt_pk_bf16(cu[m][2], cu[m][3]); *(u32x2*)(CU + off) = o2; }
	v_and_b32_e32 v0, 64, v232
	v_or_b32_e32 v2, v0, v167
	v_or_b32_e32 v0, v0, v168
	v_lshlrev_b32_e32 v2, 2, v2
	v_lshlrev_b32_e32 v8, 2, v0
	s_nop 1
	v_mov_b32_dpp v14, v48 row_ror:1 row_mask:0xf bank_mask:0xf
	v_mov_b32_dpp v9, v48 row_ror:15 row_mask:0xf bank_mask:0xf
	v_mov_b32_dpp v10, v49 row_ror:15 row_mask:0xf bank_mask:0xf
	v_mov_b32_dpp v11, v50 row_ror:15 row_mask:0xf bank_mask:0xf
	v_mov_b32_dpp v84, v32 row_ror:15 row_mask:0xf bank_mask:0xf
	v_mov_b32_dpp v85, v33 row_ror:15 row_mask:0xf bank_mask:0xf
	v_mov_b32_dpp v86, v34 row_ror:15 row_mask:0xf bank_mask:0xf
	v_mov_b32_dpp v15, v49 row_ror:1 row_mask:0xf bank_mask:0xf
	v_mov_b32_dpp v20, v50 row_ror:1 row_mask:0xf bank_mask:0xf
	v_mov_b32_dpp v21, v44 row_ror:1 row_mask:0xf bank_mask:0xf
	v_mov_b32_dpp v16, v44 row_ror:15 row_mask:0xf bank_mask:0xf
	v_mov_b32_dpp v58, v32 row_ror:1 row_mask:0xf bank_mask:0xf
	v_mov_b32_dpp v59, v33 row_ror:1 row_mask:0xf bank_mask:0xf
	v_mov_b32_dpp v61, v34 row_ror:1 row_mask:0xf bank_mask:0xf
	v_mov_b32_dpp v63, v35 row_ror:1 row_mask:0xf bank_mask:0xf
	v_mov_b32_dpp v87, v35 row_ror:15 row_mask:0xf bank_mask:0xf
	v_mov_b32_dpp v42, v28 row_ror:1 row_mask:0xf bank_mask:0xf
	v_mov_b32_dpp v60, v28 row_ror:15 row_mask:0xf bank_mask:0xf
	v_mov_b32_dpp v43, v25 row_ror:1 row_mask:0xf bank_mask:0xf
	v_mov_b32_dpp v62, v25 row_ror:15 row_mask:0xf bank_mask:0xf
	v_mov_b32_dpp v45, v22 row_ror:1 row_mask:0xf bank_mask:0xf
	v_mov_b32_dpp v82, v22 row_ror:15 row_mask:0xf bank_mask:0xf
	v_mov_b32_dpp v47, v23 row_ror:1 row_mask:0xf bank_mask:0xf
	v_mov_b32_dpp v83, v23 row_ror:15 row_mask:0xf bank_mask:0xf
	v_mov_b32_dpp v46, v13 row_ror:1 row_mask:0xf bank_mask:0xf
	v_mov_b32_dpp v12, v13 row_ror:15 row_mask:0xf bank_mask:0xf
	v_mov_b32_dpp v51, v1 row_ror:1 row_mask:0xf bank_mask:0xf
	v_mov_b32_dpp v0, v1 row_ror:15 row_mask:0xf bank_mask:0xf
	v_mov_b32_dpp v55, v5 row_ror:1 row_mask:0xf bank_mask:0xf
	v_mov_b32_dpp v4, v5 row_ror:15 row_mask:0xf bank_mask:0xf
	v_mov_b32_dpp v57, v3 row_ror:1 row_mask:0xf bank_mask:0xf
	v_mov_b32_dpp v2, v3 row_ror:15 row_mask:0xf bank_mask:0xf
	s_waitcnt lgkmcnt(14)
	v_cndmask_b32_e64 v19, v11, v86, s[6:7]
	v_cndmask_b32_e64 v17, v10, v85, s[6:7]
	v_cndmask_b32_e64 v11, v9, v84, s[6:7]
	v_mov_b32_e32 v8, v64
	v_mov_b32_e32 v9, v72
	v_mov_b32_e32 v10, v14
	v_pk_mul_f32 v[10:11], v[8:9], v[10:11]
	v_cndmask_b32_e64 v89, v16, v87, s[6:7]
	v_fma_f32 v10, v68, v48, v10
	v_add_f32_e32 v10, v10, v11
	v_mul_f32_e32 v10, v56, v10
	v_cndmask_b32_e64 v90, v10, v56, s[4:5]
	v_mov_b32_e32 v10, v65
	v_mov_b32_e32 v11, v73
	v_mov_b32_e32 v16, v15
	v_pk_mul_f32 v[16:17], v[10:11], v[16:17]
	v_mov_b32_e32 v18, v20
	v_fma_f32 v16, v69, v49, v16
	v_add_f32_e32 v16, v16, v17
	v_mul_f32_e32 v16, v52, v16
	v_cndmask_b32_e64 v91, v16, v52, s[4:5]
	v_mov_b32_e32 v16, v66
	v_mov_b32_e32 v17, v74
	v_pk_mul_f32 v[18:19], v[16:17], v[18:19]
	v_mov_b32_e32 v88, v21
	v_fma_f32 v18, v70, v50, v18
	v_add_f32_e32 v18, v18, v19
	v_mul_f32_e32 v18, v53, v18
	v_cndmask_b32_e64 v92, v18, v53, s[4:5]
	v_mov_b32_e32 v18, v67
	v_mov_b32_e32 v19, v75
	v_pk_mul_f32 v[88:89], v[18:19], v[88:89]
	s_nop 0
	v_fma_f32 v88, v71, v44, v88
	v_add_f32_e32 v88, v88, v89
	v_mul_f32_e32 v88, v54, v88
	v_cndmask_b32_e64 v89, v88, v54, s[4:5]
	v_cvt_pk_bf16_f32 v88, v90, v91
	v_lshl_add_u64 v[90:91], v[6:7], 1, s[48:49]
	v_cvt_pk_bf16_f32 v89, v92, v89
	global_store_dwordx2 v[90:91], v[88:89], off
	s_and_saveexec_b64 s[64:65], s[8:9]
	s_cbranch_execz .LBB0_314
	v_lshl_add_u64 v[90:91], v[6:7], 1, s[16:17]
	v_cvt_pk_bf16_f32 v88, v48, v49
	v_cvt_pk_bf16_f32 v89, v50, v44
	global_store_dwordx2 v[90:91], v[88:89], off

; #define PG8_STAGE(bufoff, gbase, voff) do { _Pragma("unroll") for (int _i = 0; _i < 2; ++_i) \
;         __builtin_amdgcn_global_load_lds((const unsigned*)((const char*)(gbase) + (voff)[_i]), (PG8_LAS unsigned*)(lds + (bufoff) + ldsw + _i * 8192), 16, 0, 0); } while (0)
; #define PG8_LDA(dst, b, h) do { _Pragma("unroll") for (int m = 0; m < 4; ++m) _Pragma("unroll") for (int k = 0; k < 2; ++k) dst[m][k] = *(const PG8_LAS bf16x8*)(lds + PG8_SA(b, h) + aoff + m * 2048 + k * 1024); } while (0)
; #define PG8_LDB(dst, b, h) do { _Pragma("unroll") for (int n = 0; n < 2; ++n) _Pragma("unroll") for (int k = 0; k < 2; ++k) dst[n][k] = *(const PG8_LAS bf16x8*)(lds + PG8_SB(b, h) + boff + n * 2048 + k * 1024); } while (0)
; #define PG8_SCHED __builtin_amdgcn_sched_barrier(0)
;     __host__ __device__ bool next(int i, Unit& u) const {
;         const long L = (long)i * G + c; if (L >= nwg) return false;
;         int wgid = (int)L; { const int q = nwg / NXCD, r = nwg % NXCD, xcd = wgid % NXCD, off = wgid / NXCD; wgid = (xcd < r ? xcd * (q + 1) : r * (q + 1) + (xcd - r) * q) + off; }
;         const int nig = WGM * nN, gid = wgid / nig, fm = gid * WGM, gsz = (nM - fm) < WGM ? (nM - fm) : WGM;
; template <class Epi, class Sched, bool ALIGN_EPI = false, bool SP2 = false>
; __device__ __forceinline__ void gemm_phase(PG8_LAS unsigned char* lds, const Gemm g, const Sched& S, const Epi& E) {
;     ...
;         const bool has_next = S.next(ui + 1, nxt);
;         const char* nA = has_next ? (const char*)g.A + (size_t)nxt.pm * tstep : cA; const char* nB = has_next ? (const char*)g.Bt + (size_t)nxt.pn * tstep : cB;
;         for (int t = 0; t < nt; t += 2) {
;             const bool last = (t == nt - 2);
;             const char* a1 = cA + (size_t)(t + 1) * kstep;
;             const char* a2 = last ? nA : cA + (size_t)(t + 2) * kstep; const char* b2 = last ? nB : cB + (size_t)(t + 2) * kstep;
;             const char* a3 = a2 + kstep; const char* b3 = b2 + kstep;
;             if (last && has_next) S.a_ready(nxt);
;             if constexpr (SP2) {
;             PG8_LDB(B0, 0, 0); PG8_LDB(B1, 0, 1); PG8_SCHED; PG8_LDA(At, 0, 0); PG8_STAGE(PG8_SA(1, 1), a1 + hstep, voffA);
.LBB0_337:
	v_add_u32_e32 v218, 0x10000, v167
	ds_read_b128 v[128:131], v218
	ds_read_b128 v[132:135], v218 offset:1024
	ds_read_b128 v[136:139], v218 offset:2048
	ds_read_b128 v[140:143], v218 offset:3072
	ds_read_b128 v[144:147], v218 offset:16384
	ds_read_b128 v[148:151], v218 offset:17408
	ds_read_b128 v[152:155], v218 offset:18432
	ds_read_b128 v[156:159], v218 offset:19456
	ds_read_b128 v[174:177], v204
	ds_read_b128 v[178:181], v204 offset:1024
	ds_read_b128 v[182:185], v204 offset:2048
	ds_read_b128 v[194:197], v204 offset:3072
	ds_read_b128 v[198:201], v204 offset:4096
	ds_read_b128 v[206:209], v204 offset:5120
	ds_read_b128 v[210:213], v204 offset:6144
	ds_read_b128 v[214:217], v204 offset:7168
	s_add_i32 s79, s79, 1
	s_mul_i32 s3, s79, s78
	s_mul_hi_u32 s4, s79, s74
	s_add_i32 s4, s4, s3
	s_mul_i32 s3, s79, s74
	s_add_u32 s44, s3, s2
	s_addc_u32 s45, s4, s33
	v_cmp_gt_i64_e32 vcc, s[44:45], v[192:193]
	v_cmp_lt_i64_e64 s[4:5], s[44:45], v[190:191]
	s_cbranch_vccnz .LBB0_343
	s_ashr_i32 s3, s44, 31
	s_lshr_b32 s3, s3, 29
	s_add_i32 s3, s44, s3
	s_and_b32 s7, s3, -8
	s_sub_i32 s7, s44, s7
	s_cmp_gt_i32 s7, 3
	s_mov_b64 s[44:45], -1
	s_cbranch_scc0 .LBB0_340
	s_mul_i32 s14, s7, 0xf2
	s_add_i32 s14, s14, 4
	s_mov_b64 s[44:45], 0

; #define PG8_STAGE(bufoff, gbase, voff) do { _Pragma("unroll") for (int _i = 0; _i < 2; ++_i) \
;         __builtin_amdgcn_global_load_lds((const unsigned*)((const char*)(gbase) + (voff)[_i]), (PG8_LAS unsigned*)(lds + (bufoff) + ldsw + _i * 8192), 16, 0, 0); } while (0)
; #define PG8_LDA(dst, b, h) do { _Pragma("unroll") for (int m = 0; m < 4; ++m) _Pragma("unroll") for (int k = 0; k < 2; ++k) dst[m][k] = *(const PG8_LAS bf16x8*)(lds + PG8_SA(b, h) + aoff + m * 2048 + k * 1024); } while (0)
; #define PG8_LDB(dst, b, h) do { _Pragma("unroll") for (int n = 0; n < 2; ++n) _Pragma("unroll") for (int k = 0; k < 2; ++k) dst[n][k] = *(const PG8_LAS bf16x8*)(lds + PG8_SB(b, h) + boff + n * 2048 + k * 1024); } while (0)
; #define PG8_WAIT_V(n) asm volatile("s_waitcnt vmcnt(" #n ")" ::: "memory")
; #define PG8_WAIT_L(n) asm volatile("s_waitcnt lgkmcnt(" #n ")" ::: "memory")
; #define PG8_BAR __builtin_amdgcn_s_barrier()
; #define PG8_SCHED __builtin_amdgcn_sched_barrier(0)
; template <class Epi, class Sched, bool ALIGN_EPI = false, bool SP2 = false>
; __device__ __forceinline__ void gemm_phase(PG8_LAS unsigned char* lds, const Gemm g, const Sched& S, const Epi& E) {
;     ...
;         const char* nA = has_next ? (const char*)g.A + (size_t)nxt.pm * tstep : cA; const char* nB = has_next ? (const char*)g.Bt + (size_t)nxt.pn * tstep : cB;
;         for (int t = 0; t < nt; t += 2) {
;             const bool last = (t == nt - 2);
;             const char* a1 = cA + (size_t)(t + 1) * kstep;
;             const char* a2 = last ? nA : cA + (size_t)(t + 2) * kstep; const char* b2 = last ? nB : cB + (size_t)(t + 2) * kstep;
;             const char* a3 = a2 + kstep; const char* b3 = b2 + kstep;
;             if (last && has_next) S.a_ready(nxt);
;             if constexpr (SP2) {
;             PG8_LDB(B0, 0, 0); PG8_LDB(B1, 0, 1); PG8_SCHED; PG8_LDA(At, 0, 0); PG8_STAGE(PG8_SA(1, 1), a1 + hstep, voffA);
;             PG8_WAIT_V(8); PG8_WAIT_L(0); PG8_BAR; PG8_MMA(0, 0, At, B0); PG8_MMA(0, 1, At, B1); PG8_BAR; PG8_SCHED;
;             PG8_LDA(At, 0, 1); PG8_STAGE(PG8_SB(0, 0), b2, voffB); PG8_STAGE(PG8_SB(0, 1), b2 + hstep, voffB); PG8_STAGE(PG8_SA(0, 0), a2, voffA);
;             PG8_WAIT_V(8); PG8_WAIT_L(0); PG8_BAR; PG8_MMA(1, 0, At, B0); PG8_MMA(1, 1, At, B1); PG8_BAR; PG8_SCHED;
.LBB0_343:
	s_ashr_i32 s57, s56, 31
	s_lshl_b64 s[14:15], s[56:57], 20
	s_add_u32 s44, s34, s14
	s_addc_u32 s45, s35, s15
	s_and_b64 s[14:15], s[4:5], exec
	s_cselect_b32 s7, s45, s9
	s_cselect_b32 s14, s44, s8
	s_ashr_i32 s61, s60, 31
	s_lshl_b64 s[54:55], s[60:61], 20
	s_add_u32 s58, s68, s54
	s_addc_u32 s59, s69, s55
	s_and_b64 s[54:55], s[4:5], exec
	s_cselect_b32 s15, s59, s11
	s_cselect_b32 s54, s58, s10
	s_add_u32 s8, s8, 0x80080
	s_addc_u32 s9, s9, 0
	s_add_u32 s55, s10, 0x100
	s_addc_u32 s3, s11, 0
	s_mov_b32 s57, -2
	s_nop 0
	s_add_u32 s10, s8, 0xfff80080
	s_addc_u32 s11, s9, -1
	s_add_i32 s36, 0, 0x10000
	s_cmp_eq_u32 s57, 28
	s_cselect_b32 s63, s7, s11
	s_cselect_b32 s62, s14, s10
	s_cselect_b32 s11, s15, s3
	s_cselect_b32 s10, s54, s55
	s_add_i32 s37, 0, 0x14000
	s_add_i32 m0, s53, 0xc000
	global_load_lds_dwordx4 v170, s[8:9]
	s_add_i32 m0, s53, 0xe000
	s_nop 0
	global_load_lds_dwordx4 v172, s[8:9]
	s_waitcnt lgkmcnt(0)
	s_barrier
	s_setprio 1
	s_waitcnt lgkmcnt(0)
	v_mfma_f32_16x16x32_bf16 v[124:127], v[128:131], v[174:177], 0
	v_mfma_f32_16x16x32_bf16 v[124:127], v[132:135], v[178:181], v[124:127]
	v_mfma_f32_16x16x32_bf16 v[120:123], v[136:139], v[174:177], 0
	v_mfma_f32_16x16x32_bf16 v[120:123], v[140:143], v[178:181], v[120:123]
	v_mfma_f32_16x16x32_bf16 v[108:111], v[128:131], v[182:185], 0
	v_mfma_f32_16x16x32_bf16 v[108:111], v[132:135], v[194:197], v[108:111]
	v_mfma_f32_16x16x32_bf16 v[104:107], v[136:139], v[182:185], 0
	v_mfma_f32_16x16x32_bf16 v[104:107], v[140:143], v[194:197], v[104:107]
	v_mfma_f32_16x16x32_bf16 v[92:95], v[128:131], v[198:201], 0
	v_mfma_f32_16x16x32_bf16 v[92:95], v[132:135], v[206:209], v[92:95]
	v_mfma_f32_16x16x32_bf16 v[88:91], v[136:139], v[198:201], 0
	v_mfma_f32_16x16x32_bf16 v[88:91], v[140:143], v[206:209], v[88:91]
	v_mfma_f32_16x16x32_bf16 v[76:79], v[128:131], v[210:213], 0
	v_mfma_f32_16x16x32_bf16 v[76:79], v[132:135], v[214:217], v[76:79]
	v_mfma_f32_16x16x32_bf16 v[72:75], v[136:139], v[210:213], 0
	v_mfma_f32_16x16x32_bf16 v[72:75], v[140:143], v[214:217], v[72:75]
	s_setprio 0
	s_setprio 1
	v_mfma_f32_16x16x32_bf16 v[116:119], v[144:147], v[174:177], 0
	v_mfma_f32_16x16x32_bf16 v[116:119], v[148:151], v[178:181], v[116:119]
	v_mfma_f32_16x16x32_bf16 v[112:115], v[152:155], v[174:177], 0
	v_mfma_f32_16x16x32_bf16 v[112:115], v[156:159], v[178:181], v[112:115]
	v_mfma_f32_16x16x32_bf16 v[100:103], v[144:147], v[182:185], 0
	v_mfma_f32_16x16x32_bf16 v[100:103], v[148:151], v[194:197], v[100:103]
	v_mfma_f32_16x16x32_bf16 v[96:99], v[152:155], v[182:185], 0
	v_mfma_f32_16x16x32_bf16 v[96:99], v[156:159], v[194:197], v[96:99]
	v_mfma_f32_16x16x32_bf16 v[84:87], v[144:147], v[198:201], 0
	v_mfma_f32_16x16x32_bf16 v[84:87], v[148:151], v[206:209], v[84:87]
	v_mfma_f32_16x16x32_bf16 v[80:83], v[152:155], v[198:201], 0
	v_mfma_f32_16x16x32_bf16 v[80:83], v[156:159], v[206:209], v[80:83]
	v_mfma_f32_16x16x32_bf16 v[68:71], v[144:147], v[210:213], 0
	v_mfma_f32_16x16x32_bf16 v[68:71], v[148:151], v[214:217], v[68:71]
	v_mfma_f32_16x16x32_bf16 v[64:67], v[152:155], v[210:213], 0
	v_mfma_f32_16x16x32_bf16 v[64:67], v[156:159], v[214:217], v[64:67]
	s_setprio 0
	s_barrier
	s_add_i32 s36, s36, s70
	s_mov_b32 m0, s36
	ds_read_b128 v[174:177], v204 offset:16384
	ds_read_b128 v[178:181], v204 offset:17408
	ds_read_b128 v[182:185], v204 offset:18432
	ds_read_b128 v[194:197], v204 offset:19456
	ds_read_b128 v[198:201], v204 offset:20480
	ds_read_b128 v[206:209], v204 offset:21504
	ds_read_b128 v[210:213], v204 offset:22528
	ds_read_b128 v[214:217], v204 offset:23552
	global_load_lds_dwordx4 v160, s[10:11]
	s_add_i32 m0, s36, 0x2000
	s_add_u32 s64, s10, 0x80000
	s_addc_u32 s65, s11, 0
	s_add_i32 s36, s37, s70
	global_load_lds_dwordx4 v162, s[10:11]
	s_mov_b32 m0, s36
	s_nop 0
	global_load_lds_dwordx4 v160, s[64:65]
	s_add_i32 m0, s36, 0x2000
	s_nop 0
	global_load_lds_dwordx4 v162, s[64:65]
	s_mov_b32 m0, s53
	s_nop 0
	global_load_lds_dwordx4 v160, s[62:63]
	s_mov_b32 m0, s71
	s_nop 0
	global_load_lds_dwordx4 v162, s[62:63]
	s_waitcnt lgkmcnt(0)
	s_barrier
	s_setprio 1
	s_waitcnt lgkmcnt(0)
	v_mfma_f32_16x16x32_bf16 v[60:63], v[128:131], v[174:177], 0
	v_mfma_f32_16x16x32_bf16 v[60:63], v[132:135], v[178:181], v[60:63]
	v_mfma_f32_16x16x32_bf16 v[56:59], v[136:139], v[174:177], 0
	v_mfma_f32_16x16x32_bf16 v[56:59], v[140:143], v[178:181], v[56:59]
	v_mfma_f32_16x16x32_bf16 v[44:47], v[128:131], v[182:185], 0
	v_mfma_f32_16x16x32_bf16 v[44:47], v[132:135], v[194:197], v[44:47]
	v_mfma_f32_16x16x32_bf16 v[40:43], v[136:139], v[182:185], 0
	v_mfma_f32_16x16x32_bf16 v[40:43], v[140:143], v[194:197], v[40:43]
	v_mfma_f32_16x16x32_bf16 v[28:31], v[128:131], v[198:201], 0
	v_mfma_f32_16x16x32_bf16 v[28:31], v[132:135], v[206:209], v[28:31]
	v_mfma_f32_16x16x32_bf16 v[24:27], v[136:139], v[198:201], 0
	v_mfma_f32_16x16x32_bf16 v[24:27], v[140:143], v[206:209], v[24:27]
	v_mfma_f32_16x16x32_bf16 v[12:15], v[128:131], v[210:213], 0
	v_mfma_f32_16x16x32_bf16 v[12:15], v[132:135], v[214:217], v[12:15]
	v_mfma_f32_16x16x32_bf16 v[8:11], v[136:139], v[210:213], 0
	v_mfma_f32_16x16x32_bf16 v[8:11], v[140:143], v[214:217], v[8:11]
	s_setprio 0
	s_setprio 1
	v_mfma_f32_16x16x32_bf16 v[52:55], v[144:147], v[174:177], 0
	v_mfma_f32_16x16x32_bf16 v[52:55], v[148:151], v[178:181], v[52:55]
	v_mfma_f32_16x16x32_bf16 v[48:51], v[152:155], v[174:177], 0
	v_mfma_f32_16x16x32_bf16 v[48:51], v[156:159], v[178:181], v[48:51]
	v_mfma_f32_16x16x32_bf16 v[36:39], v[144:147], v[182:185], 0
	v_mfma_f32_16x16x32_bf16 v[36:39], v[148:151], v[194:197], v[36:39]
	v_mfma_f32_16x16x32_bf16 v[32:35], v[152:155], v[182:185], 0
	v_mfma_f32_16x16x32_bf16 v[32:35], v[156:159], v[194:197], v[32:35]
	v_mfma_f32_16x16x32_bf16 v[20:23], v[144:147], v[198:201], 0
	v_mfma_f32_16x16x32_bf16 v[20:23], v[148:151], v[206:209], v[20:23]
	v_mfma_f32_16x16x32_bf16 v[16:19], v[152:155], v[198:201], 0
	v_mfma_f32_16x16x32_bf16 v[16:19], v[156:159], v[206:209], v[16:19]
	v_mfma_f32_16x16x32_bf16 v[4:7], v[144:147], v[210:213], 0
	v_mfma_f32_16x16x32_bf16 v[4:7], v[148:151], v[214:217], v[4:7]
	v_mfma_f32_16x16x32_bf16 v[0:3], v[152:155], v[210:213], 0
	v_mfma_f32_16x16x32_bf16 v[0:3], v[156:159], v[214:217], v[0:3]
	s_setprio 0
	s_barrier
; #define PG8_STAGE(bufoff, gbase, voff) do { _Pragma("unroll") for (int _i = 0; _i < 2; ++_i) \
;         __builtin_amdgcn_global_load_lds((const unsigned*)((const char*)(gbase) + (voff)[_i]), (PG8_LAS unsigned*)(lds + (bufoff) + ldsw + _i * 8192), 16, 0, 0); } while (0)
; #define PG8_LDA(dst, b, h) do { _Pragma("unroll") for (int m = 0; m < 4; ++m) _Pragma("unroll") for (int k = 0; k < 2; ++k) dst[m][k] = *(const PG8_LAS bf16x8*)(lds + PG8_SA(b, h) + aoff + m * 2048 + k * 1024); } while (0)
; #define PG8_LDB(dst, b, h) do { _Pragma("unroll") for (int n = 0; n < 2; ++n) _Pragma("unroll") for (int k = 0; k < 2; ++k) dst[n][k] = *(const PG8_LAS bf16x8*)(lds + PG8_SB(b, h) + boff + n * 2048 + k * 1024); } while (0)
; #define PG8_MMA(ai, bj, At, Bt) do { __builtin_amdgcn_s_setprio(1); _Pragma("unroll") for (int m = 0; m < 4; ++m) _Pragma("unroll") for (int n = 0; n < 2; ++n) _Pragma("unroll") for (int k = 0; k < 2; ++k) \
;         acc[ai][bj][m][n] = __builtin_amdgcn_mfma_f32_16x16x32_bf16(Bt[n][k], At[m][k], acc[ai][bj][m][n], 0, 0, 0); __builtin_amdgcn_s_setprio(0); } while (0)
; #define PG8_WAIT_V(n) asm volatile("s_waitcnt vmcnt(" #n ")" ::: "memory")
; #define PG8_WAIT_L(n) asm volatile("s_waitcnt lgkmcnt(" #n ")" ::: "memory")
; #define PG8_BAR __builtin_amdgcn_s_barrier()
; #define PG8_SCHED __builtin_amdgcn_sched_barrier(0)
; template <class Epi, class Sched, bool ALIGN_EPI = false, bool SP2 = false>
; __device__ __forceinline__ void gemm_phase(PG8_LAS unsigned char* lds, const Gemm g, const Sched& S, const Epi& E) {
;     ...
;             PG8_LDB(B0, 1, 0); PG8_LDB(B1, 1, 1); PG8_SCHED; PG8_LDA(At, 1, 0); PG8_STAGE(PG8_SA(0, 1), a2 + hstep, voffA);
;             PG8_WAIT_V(8); PG8_WAIT_L(0); PG8_BAR; PG8_MMA(0, 0, At, B0); PG8_MMA(0, 1, At, B1); PG8_BAR; PG8_SCHED;
;             PG8_LDA(At, 1, 1); PG8_STAGE(PG8_SB(1, 0), b3, voffB); PG8_STAGE(PG8_SB(1, 1), b3 + hstep, voffB); PG8_STAGE(PG8_SA(1, 0), a3, voffA);
;             PG8_WAIT_V(8); PG8_WAIT_L(0); PG8_BAR; PG8_MMA(1, 0, At, B0); PG8_MMA(1, 1, At, B1); PG8_BAR; PG8_SCHED;
	s_add_i32 s36, 0, 0x18000
	s_add_i32 s37, 0, 0x1c000
	ds_read_b128 v[128:131], v218 offset:32768
	ds_read_b128 v[132:135], v218 offset:33792
	ds_read_b128 v[136:139], v218 offset:34816
	ds_read_b128 v[140:143], v218 offset:35840
	ds_read_b128 v[144:147], v218 offset:49152
	ds_read_b128 v[148:151], v218 offset:50176
	ds_read_b128 v[152:155], v218 offset:51200
	ds_read_b128 v[156:159], v218 offset:52224
	s_add_u32 s62, s62, 0x80000
	s_addc_u32 s63, s63, 0
	s_mov_b32 m0, s72
	ds_read_b128 v[174:177], v204 offset:32768
	ds_read_b128 v[178:181], v204 offset:33792
	ds_read_b128 v[182:185], v204 offset:34816
	ds_read_b128 v[194:197], v204 offset:35840
	ds_read_b128 v[198:201], v204 offset:36864
	ds_read_b128 v[206:209], v204 offset:37888
	ds_read_b128 v[210:213], v204 offset:38912
	ds_read_b128 v[214:217], v204 offset:39936
	global_load_lds_dwordx4 v160, s[62:63]
	s_mov_b32 m0, s73
	s_nop 0
	global_load_lds_dwordx4 v162, s[62:63]
	s_waitcnt vmcnt(8)
	s_waitcnt lgkmcnt(0)
	s_barrier
	s_setprio 1
	s_waitcnt lgkmcnt(0)
	v_mfma_f32_16x16x32_bf16 v[124:127], v[128:131], v[174:177], v[124:127]
	v_mfma_f32_16x16x32_bf16 v[124:127], v[132:135], v[178:181], v[124:127]
	v_mfma_f32_16x16x32_bf16 v[120:123], v[136:139], v[174:177], v[120:123]
	v_mfma_f32_16x16x32_bf16 v[120:123], v[140:143], v[178:181], v[120:123]
	v_mfma_f32_16x16x32_bf16 v[108:111], v[128:131], v[182:185], v[108:111]
	v_mfma_f32_16x16x32_bf16 v[108:111], v[132:135], v[194:197], v[108:111]
	v_mfma_f32_16x16x32_bf16 v[104:107], v[136:139], v[182:185], v[104:107]
	v_mfma_f32_16x16x32_bf16 v[104:107], v[140:143], v[194:197], v[104:107]
	v_mfma_f32_16x16x32_bf16 v[92:95], v[128:131], v[198:201], v[92:95]
	v_mfma_f32_16x16x32_bf16 v[92:95], v[132:135], v[206:209], v[92:95]
	v_mfma_f32_16x16x32_bf16 v[88:91], v[136:139], v[198:201], v[88:91]
	v_mfma_f32_16x16x32_bf16 v[88:91], v[140:143], v[206:209], v[88:91]
	v_mfma_f32_16x16x32_bf16 v[76:79], v[128:131], v[210:213], v[76:79]
	v_mfma_f32_16x16x32_bf16 v[76:79], v[132:135], v[214:217], v[76:79]
	v_mfma_f32_16x16x32_bf16 v[72:75], v[136:139], v[210:213], v[72:75]
	v_mfma_f32_16x16x32_bf16 v[72:75], v[140:143], v[214:217], v[72:75]
	s_setprio 0
	s_setprio 1
	v_mfma_f32_16x16x32_bf16 v[116:119], v[144:147], v[174:177], v[116:119]
	v_mfma_f32_16x16x32_bf16 v[116:119], v[148:151], v[178:181], v[116:119]
	v_mfma_f32_16x16x32_bf16 v[112:115], v[152:155], v[174:177], v[112:115]
	v_mfma_f32_16x16x32_bf16 v[112:115], v[156:159], v[178:181], v[112:115]
	v_mfma_f32_16x16x32_bf16 v[100:103], v[144:147], v[182:185], v[100:103]
	v_mfma_f32_16x16x32_bf16 v[100:103], v[148:151], v[194:197], v[100:103]
	v_mfma_f32_16x16x32_bf16 v[96:99], v[152:155], v[182:185], v[96:99]
	v_mfma_f32_16x16x32_bf16 v[96:99], v[156:159], v[194:197], v[96:99]
	v_mfma_f32_16x16x32_bf16 v[84:87], v[144:147], v[198:201], v[84:87]
	v_mfma_f32_16x16x32_bf16 v[84:87], v[148:151], v[206:209], v[84:87]
	v_mfma_f32_16x16x32_bf16 v[80:83], v[152:155], v[198:201], v[80:83]
	v_mfma_f32_16x16x32_bf16 v[80:83], v[156:159], v[206:209], v[80:83]
	v_mfma_f32_16x16x32_bf16 v[68:71], v[144:147], v[210:213], v[68:71]
	v_mfma_f32_16x16x32_bf16 v[68:71], v[148:151], v[214:217], v[68:71]
	v_mfma_f32_16x16x32_bf16 v[64:67], v[152:155], v[210:213], v[64:67]
	v_mfma_f32_16x16x32_bf16 v[64:67], v[156:159], v[214:217], v[64:67]
	s_setprio 0
	s_barrier
	s_add_i32 s36, s36, s70
	s_mov_b32 m0, s36
	ds_read_b128 v[174:177], v204 offset:49152
	ds_read_b128 v[178:181], v204 offset:50176
	ds_read_b128 v[182:185], v204 offset:51200
	ds_read_b128 v[194:197], v204 offset:52224
	ds_read_b128 v[198:201], v204 offset:53248
	ds_read_b128 v[206:209], v204 offset:54272
	ds_read_b128 v[210:213], v204 offset:55296
	ds_read_b128 v[214:217], v204 offset:56320
	s_add_u32 s100, s10, 0x80
	s_addc_u32 s101, s11, 0
	global_load_lds_dwordx4 v160, s[100:101]
	s_add_i32 m0, s36, 0x2000
	s_add_u32 s10, s10, 0x80080
	s_addc_u32 s11, s11, 0
	s_add_i32 s36, s37, s70
	s_add_u32 s100, s10, 0xfff80000
	s_addc_u32 s101, s11, -1
	global_load_lds_dwordx4 v162, s[100:101]
	s_mov_b32 m0, s36
	s_nop 0
	global_load_lds_dwordx4 v160, s[10:11]
	s_add_i32 m0, s36, 0x2000
	s_nop 0
	global_load_lds_dwordx4 v162, s[10:11]
	s_mov_b32 m0, s76
	s_nop 0
	s_add_u32 s100, s62, 0xfff80080
	s_addc_u32 s101, s63, -1
	global_load_lds_dwordx4 v160, s[100:101]
	s_mov_b32 m0, s77
	s_nop 0
	global_load_lds_dwordx4 v162, s[100:101]
	s_waitcnt vmcnt(8)
	s_waitcnt lgkmcnt(0)
	s_barrier
	s_setprio 1
	s_waitcnt lgkmcnt(0)
	v_mfma_f32_16x16x32_bf16 v[60:63], v[128:131], v[174:177], v[60:63]
	v_mfma_f32_16x16x32_bf16 v[60:63], v[132:135], v[178:181], v[60:63]
	v_mfma_f32_16x16x32_bf16 v[56:59], v[136:139], v[174:177], v[56:59]
	v_mfma_f32_16x16x32_bf16 v[56:59], v[140:143], v[178:181], v[56:59]
	v_mfma_f32_16x16x32_bf16 v[44:47], v[128:131], v[182:185], v[44:47]
	v_mfma_f32_16x16x32_bf16 v[44:47], v[132:135], v[194:197], v[44:47]
	v_mfma_f32_16x16x32_bf16 v[40:43], v[136:139], v[182:185], v[40:43]
	v_mfma_f32_16x16x32_bf16 v[40:43], v[140:143], v[194:197], v[40:43]
	v_mfma_f32_16x16x32_bf16 v[28:31], v[128:131], v[198:201], v[28:31]
	v_mfma_f32_16x16x32_bf16 v[28:31], v[132:135], v[206:209], v[28:31]
	v_mfma_f32_16x16x32_bf16 v[24:27], v[136:139], v[198:201], v[24:27]
	v_mfma_f32_16x16x32_bf16 v[24:27], v[140:143], v[206:209], v[24:27]
	v_mfma_f32_16x16x32_bf16 v[12:15], v[128:131], v[210:213], v[12:15]
	v_mfma_f32_16x16x32_bf16 v[12:15], v[132:135], v[214:217], v[12:15]
	v_mfma_f32_16x16x32_bf16 v[8:11], v[136:139], v[210:213], v[8:11]
	v_mfma_f32_16x16x32_bf16 v[8:11], v[140:143], v[214:217], v[8:11]
	s_setprio 0
	s_setprio 1
	v_mfma_f32_16x16x32_bf16 v[52:55], v[144:147], v[174:177], v[52:55]
	v_mfma_f32_16x16x32_bf16 v[52:55], v[148:151], v[178:181], v[52:55]
	v_mfma_f32_16x16x32_bf16 v[48:51], v[152:155], v[174:177], v[48:51]
	v_mfma_f32_16x16x32_bf16 v[48:51], v[156:159], v[178:181], v[48:51]
	v_mfma_f32_16x16x32_bf16 v[36:39], v[144:147], v[182:185], v[36:39]
	v_mfma_f32_16x16x32_bf16 v[36:39], v[148:151], v[194:197], v[36:39]
	v_mfma_f32_16x16x32_bf16 v[32:35], v[152:155], v[182:185], v[32:35]
	v_mfma_f32_16x16x32_bf16 v[32:35], v[156:159], v[194:197], v[32:35]
	v_mfma_f32_16x16x32_bf16 v[20:23], v[144:147], v[198:201], v[20:23]
	v_mfma_f32_16x16x32_bf16 v[20:23], v[148:151], v[206:209], v[20:23]
	v_mfma_f32_16x16x32_bf16 v[16:19], v[152:155], v[198:201], v[16:19]
	v_mfma_f32_16x16x32_bf16 v[16:19], v[156:159], v[206:209], v[16:19]
	v_mfma_f32_16x16x32_bf16 v[4:7], v[144:147], v[210:213], v[4:7]
	v_mfma_f32_16x16x32_bf16 v[4:7], v[148:151], v[214:217], v[4:7]
	v_mfma_f32_16x16x32_bf16 v[0:3], v[152:155], v[210:213], v[0:3]
	v_mfma_f32_16x16x32_bf16 v[0:3], v[156:159], v[214:217], v[0:3]
	s_setprio 0
	s_barrier
	s_add_i32 s57, s57, 2
	s_add_u32 s8, s8, 0x100
	s_addc_u32 s9, s9, 0
	s_add_u32 s55, s55, 0x100
	s_addc_u32 s3, s3, 0
	s_cmp_gt_u32 s57, 29
